# also non-temporal loads of the sgu, pool and final-norm inputs (read for the last time there)
# baseline (speedup 1.0000x reference)
.LBB0_350:
	s_or_b64 exec, exec, s[8:9]
	s_mov_b64 s[8:9], s[0:1]
	v_mov_b32_e32 v134, v157
	s_waitcnt lgkmcnt(0)
	s_barrier
	s_cmpk_gt_i32 s2, 0x7ff
	v_readfirstlane_b32 s14, v134
	s_cbranch_scc1 .LBB0_369
	s_load_dwordx2 s[10:11], s[8:9], 0x80
	s_load_dwordx4 s[20:23], s[8:9], 0x30
	s_load_dwordx2 s[26:27], s[8:9], 0x40
	v_mov_b32_e32 v1, 0
	v_mov_b32_e32 v2, v1
	v_mov_b32_e32 v3, v1
	s_movk_i32 s3, 0x80
	s_waitcnt lgkmcnt(0)
	s_add_u32 s28, s10, 0x200000
	v_mov_b32_e32 v0, v1
	v_mov_b64_e32 v[6:7], v[2:3]
	v_mov_b64_e32 v[10:11], v[2:3]
	v_cmp_gt_i32_e64 s[8:9], s3, v134
	s_addc_u32 s29, s11, 0
	s_and_b32 s3, s73, 0xffffff80
	s_mov_b32 s31, 0
	v_mov_b64_e32 v[4:5], v[0:1]
	v_mov_b64_e32 v[8:9], v[0:1]
	s_and_saveexec_b64 s[12:13], s[8:9]
	s_cbranch_execz .LBB0_353
	v_add_u32_e32 v2, s3, v134
	v_ashrrev_i32_e32 v3, 31, v2
	v_lshlrev_b64 v[2:3], 5, v[2:3]
	v_lshl_add_u64 v[2:3], s[28:29], 0, v[2:3]
	global_load_dwordx4 v[4:7], v[2:3], off offset:16 nt
	global_load_dwordx4 v[8:11], v[2:3], off nt
.LBB0_353:
	s_or_b64 exec, exec, s[12:13]
	s_add_u32 s44, s10, 0xa000000
	s_addc_u32 s45, s11, 0
	s_add_u32 s12, s10, 0x12000000
	s_addc_u32 s13, s11, 0
	s_ashr_i32 s10, s14, 1
	s_and_b32 s46, s10, 0xffffffe0
	s_and_b32 s10, s72, 0x700
	s_ashr_i32 s47, s46, 31
	s_lshl_b32 s16, s10, 1
	v_and_b32_e32 v135, 15, v134
	s_add_u32 s10, s44, s16
	s_addc_u32 s11, s45, 0
	s_lshl_b64 s[14:15], s[46:47], 1
	v_or_b32_e32 v20, s3, v135
	v_bfe_u32 v66, v134, 4, 2
	s_add_u32 s10, s10, s14
	v_or_b32_e32 v12, 0x70, v20
	s_addc_u32 s11, s11, s15
	v_lshlrev_b32_e32 v0, 4, v66
	v_ashrrev_i32_e32 v13, 31, v12
	v_lshl_add_u64 v[2:3], s[10:11], 0, v[0:1]
	v_lshlrev_b64 v[12:13], 12, v[12:13]
	v_lshl_add_u64 v[22:23], v[2:3], 0, v[12:13]
	v_or_b32_e32 v12, 0x60, v20
	v_ashrrev_i32_e32 v13, 31, v12
	v_lshlrev_b64 v[12:13], 12, v[12:13]
	v_lshl_add_u64 v[24:25], v[2:3], 0, v[12:13]
	global_load_dwordx4 v[12:15], v[22:23], off nt
	global_load_dwordx4 v[16:19], v[24:25], off nt
	v_or_b32_e32 v22, 0x50, v20
	v_ashrrev_i32_e32 v23, 31, v22
	v_or_b32_e32 v24, 64, v20
	v_lshlrev_b64 v[22:23], 12, v[22:23]
	v_ashrrev_i32_e32 v25, 31, v24
	v_lshl_add_u64 v[22:23], v[2:3], 0, v[22:23]
	v_lshlrev_b64 v[24:25], 12, v[24:25]
	v_lshl_add_u64 v[24:25], v[2:3], 0, v[24:25]
	global_load_dwordx4 v[48:51], v[22:23], off nt
	global_load_dwordx4 v[56:59], v[24:25], off nt
	v_or_b32_e32 v22, 48, v20
	v_ashrrev_i32_e32 v23, 31, v22
	v_or_b32_e32 v24, 32, v20
	v_lshlrev_b64 v[22:23], 12, v[22:23]
	v_ashrrev_i32_e32 v25, 31, v24
	v_lshl_add_u64 v[22:23], v[2:3], 0, v[22:23]
	v_lshlrev_b64 v[24:25], 12, v[24:25]
	v_lshl_add_u64 v[24:25], v[2:3], 0, v[24:25]
	global_load_dwordx4 v[68:71], v[22:23], off nt
	global_load_dwordx4 v[72:75], v[24:25], off nt
	v_or_b32_e32 v22, 16, v20
	v_ashrrev_i32_e32 v23, 31, v22
	v_lshlrev_b64 v[22:23], 12, v[22:23]
	v_ashrrev_i32_e32 v21, 31, v20
	v_lshlrev_b32_e32 v136, 3, v134
	v_ashrrev_i32_e32 v138, 5, v134
	v_lshl_add_u64 v[22:23], v[2:3], 0, v[22:23]
	v_lshlrev_b64 v[20:21], 12, v[20:21]
	v_and_b32_e32 v137, 0xf8, v136
	v_lshl_add_u64 v[2:3], v[2:3], 0, v[20:21]
	global_load_dwordx4 v[76:79], v[22:23], off nt
	global_load_dwordx4 v[80:83], v[2:3], off nt
	s_add_u32 s10, s12, s16
	v_add_u32_e32 v22, s3, v138
	s_addc_u32 s11, s13, 0
	v_lshlrev_b32_e32 v2, 1, v137
	v_mov_b32_e32 v3, v1
	v_ashrrev_i32_e32 v23, 31, v22
	v_lshl_add_u64 v[20:21], s[10:11], 0, v[2:3]
	v_lshlrev_b64 v[22:23], 12, v[22:23]
	v_lshl_add_u64 v[60:61], v[20:21], 0, v[22:23]
	s_mov_b32 s3, 0x70000
	v_add_co_u32_e32 v62, vcc, s3, v60
	s_mov_b32 s35, 0x60000
	s_nop 0
	v_addc_co_u32_e32 v63, vcc, 0, v61, vcc
	v_add_co_u32_e32 v24, vcc, s35, v60
	s_mov_b32 s52, 0x50000
	s_nop 0
	v_addc_co_u32_e32 v25, vcc, 0, v61, vcc
	v_add_co_u32_e32 v26, vcc, s52, v60
	s_mov_b32 s53, 0x40000
	s_nop 0
	v_addc_co_u32_e32 v27, vcc, 0, v61, vcc
	global_load_dwordx4 v[36:39], v[24:25], off nt
	global_load_dwordx4 v[20:23], v[26:27], off nt
	v_add_co_u32_e32 v24, vcc, s53, v60
	s_mov_b32 s54, 0x30000
	s_nop 0
	v_addc_co_u32_e32 v25, vcc, 0, v61, vcc
	v_add_co_u32_e32 v26, vcc, s54, v60
	s_mov_b32 s55, 0x20000
	s_nop 0
	v_addc_co_u32_e32 v27, vcc, 0, v61, vcc
	global_load_dwordx4 v[40:43], v[24:25], off nt
	global_load_dwordx4 v[28:31], v[26:27], off nt
	v_add_co_u32_e32 v24, vcc, s55, v60
	s_mov_b32 s56, 0x10000
	s_nop 0
	v_addc_co_u32_e32 v25, vcc, 0, v61, vcc
	v_add_co_u32_e32 v64, vcc, s56, v60
	s_add_i32 s16, 0, 0x18a00
	s_nop 0
	v_addc_co_u32_e32 v65, vcc, 0, v61, vcc
	global_load_dwordx4 v[44:47], v[24:25], off nt
	global_load_dwordx4 v[32:35], v[64:65], off nt
	global_load_dwordx4 v[52:55], v[62:63], off nt
	s_nop 0
	global_load_dwordx4 v[24:27], v[60:61], off nt
	v_lshlrev_b32_e32 v62, 1, v134
	v_add_u32_e32 v61, 0, v2
	v_lshl_add_u64 v[2:3], s[12:13], 0, v[2:3]
	s_add_u32 s12, s44, s14
	v_and_b32_e32 v62, 24, v62
	v_and_b32_e32 v63, 3, v134
	s_addc_u32 s13, s45, s15
	v_or3_b32 v62, v62, v63, s46
	v_lshl_add_u64 v[128:129], s[12:13], 0, v[0:1]
	s_add_i32 s57, 0, 0x10200
	s_movk_i32 s12, 0x204
	v_lshlrev_b32_e32 v62, 1, v62
	v_mul_u32_u24_e32 v64, 0x1020, v66
	v_lshlrev_b32_e32 v60, 3, v66
	s_movk_i32 s10, 0x800
	v_add_u32_e32 v0, s57, v0
	v_lshl_add_u32 v140, v138, 2, s16
	v_mul_lo_u32 v63, v138, s12
	v_add3_u32 v148, 0, v62, v64
	v_mul_u32_u24_e32 v62, 0x110, v135
	v_cmp_gt_i32_e64 s[10:11], s10, v134
	v_lshl_add_u32 v139, v134, 2, s16
	v_add_u32_e32 v141, 64, v140
	v_add_u32_e32 v142, 0x80, v140
	v_add_u32_e32 v143, 0xc0, v140
	v_add_u32_e32 v144, 0x100, v140
	v_add_u32_e32 v145, 0x140, v140
	v_add_u32_e32 v146, 0x180, v140
	v_add_u32_e32 v147, 0x1c0, v140
	s_movk_i32 s58, 0x110
	s_mov_b32 s16, -1
	s_movk_i32 s59, 0x5ff
	v_mov_b32_e32 v149, 0x358637bd
	v_add_u32_e32 v150, v61, v63
	v_lshlrev_b32_e32 v130, 1, v60
	v_add_u32_e32 v151, v0, v62
	s_mov_b32 s60, s2
	v_mov_b32_e32 v60, v1
	v_mov_b32_e32 v61, v1
	v_mov_b32_e32 v62, v1
	v_mov_b32_e32 v63, v1
	v_mov_b32_e32 v64, v1
	v_mov_b32_e32 v65, v1
	v_mov_b32_e32 v66, v1
	v_mov_b32_e32 v67, v1
	s_branch .LBB0_356
.LBB0_354:
	s_or_b64 exec, exec, s[14:15]
	v_add_u32_e32 v20, s48, v138
	s_lshl_b32 s14, s17, 9
	s_and_b32 s30, s14, 0xe00
	v_ashrrev_i32_e32 v21, 31, v20
	v_lshl_add_u64 v[22:23], v[2:3], 0, s[30:31]
	v_lshlrev_b64 v[20:21], 12, v[20:21]
	v_lshl_add_u64 v[36:37], v[22:23], 0, v[20:21]
	v_add_co_u32_e32 v20, vcc, 0x10000, v36
	v_or_b32_e32 v108, s48, v135
	s_nop 0
	v_addc_co_u32_e32 v21, vcc, 0, v37, vcc
	global_load_dwordx4 v[24:27], v[36:37], off nt
	global_load_dwordx4 v[32:35], v[20:21], off nt
	v_add_co_u32_e32 v20, vcc, s55, v36
	v_ashrrev_i32_e32 v109, 31, v108
	s_nop 0
	v_addc_co_u32_e32 v21, vcc, 0, v37, vcc
	v_add_co_u32_e32 v22, vcc, s54, v36
	v_lshlrev_b64 v[84:85], 12, v[108:109]
	s_nop 0
	v_addc_co_u32_e32 v23, vcc, 0, v37, vcc
	global_load_dwordx4 v[44:47], v[20:21], off nt
	global_load_dwordx4 v[28:31], v[22:23], off nt
	v_add_co_u32_e32 v20, vcc, s53, v36
	v_or_b32_e32 v86, 16, v108
	s_nop 0
	v_addc_co_u32_e32 v21, vcc, 0, v37, vcc
	v_add_co_u32_e32 v22, vcc, s52, v36
	v_or_b32_e32 v92, 32, v108
	s_nop 0
	v_addc_co_u32_e32 v23, vcc, 0, v37, vcc
	v_add_co_u32_e32 v38, vcc, s35, v36
	v_or_b32_e32 v94, 48, v108
	v_or_b32_e32 v100, 64, v108
	v_or_b32_e32 v102, 0x50, v108
	v_or_b32_e32 v112, 0x60, v108
	v_or_b32_e32 v108, 0x70, v108
	v_addc_co_u32_e32 v39, vcc, 0, v37, vcc
	v_ashrrev_i32_e32 v87, 31, v86
	v_ashrrev_i32_e32 v93, 31, v92
	v_ashrrev_i32_e32 v95, 31, v94
	v_ashrrev_i32_e32 v101, 31, v100
	v_ashrrev_i32_e32 v103, 31, v102
	v_ashrrev_i32_e32 v113, 31, v112
	v_ashrrev_i32_e32 v109, 31, v108
	v_add_co_u32_e32 v52, vcc, s3, v36
	v_lshl_add_u64 v[110:111], v[128:129], 0, s[30:31]
	v_lshlrev_b64 v[86:87], 12, v[86:87]
	v_lshlrev_b64 v[92:93], 12, v[92:93]
	v_lshlrev_b64 v[94:95], 12, v[94:95]
	v_lshlrev_b64 v[100:101], 12, v[100:101]
	v_lshlrev_b64 v[102:103], 12, v[102:103]
	v_lshlrev_b64 v[112:113], 12, v[112:113]
	v_lshlrev_b64 v[108:109], 12, v[108:109]
	v_addc_co_u32_e32 v53, vcc, 0, v37, vcc
	v_lshl_add_u64 v[84:85], v[110:111], 0, v[84:85]
	v_lshl_add_u64 v[88:89], v[110:111], 0, v[86:87]
	v_lshl_add_u64 v[92:93], v[110:111], 0, v[92:93]
	v_lshl_add_u64 v[96:97], v[110:111], 0, v[94:95]
	v_lshl_add_u64 v[100:101], v[110:111], 0, v[100:101]
	v_lshl_add_u64 v[104:105], v[110:111], 0, v[102:103]
	v_lshl_add_u64 v[112:113], v[110:111], 0, v[112:113]
	v_lshl_add_u64 v[114:115], v[110:111], 0, v[108:109]
	global_load_dwordx4 v[40:43], v[20:21], off nt
	s_nop 0
	global_load_dwordx4 v[20:23], v[22:23], off nt
	s_nop 0
	global_load_dwordx4 v[36:39], v[38:39], off nt
	s_nop 0
	global_load_dwordx4 v[52:55], v[52:53], off nt
	s_nop 0
	global_load_dwordx4 v[84:87], v[84:85], off nt
	s_nop 0
	global_load_dwordx4 v[88:91], v[88:89], off nt
	s_nop 0
	global_load_dwordx4 v[92:95], v[92:93], off nt
	s_nop 0
	global_load_dwordx4 v[96:99], v[96:97], off nt
	s_nop 0
	global_load_dwordx4 v[100:103], v[100:101], off nt
	s_nop 0
	global_load_dwordx4 v[104:107], v[104:105], off nt
	s_nop 0
	global_load_dwordx4 v[108:111], v[112:113], off nt
	s_nop 0
	global_load_dwordx4 v[112:115], v[114:115], off nt

.LBB0_361:
	v_ashrrev_i32_e32 v88, 4, v61
	v_ashrrev_i32_e32 v89, 31, v88
	v_lshl_add_u64 v[62:63], v[88:89], 0, s[30:31]
	v_and_b32_e32 v90, 0x78, v60
	v_lshlrev_b64 v[62:63], 9, v[62:63]
	v_lshlrev_b32_e32 v0, 2, v90
	v_lshl_add_u64 v[62:63], s[22:23], 0, v[62:63]
	v_lshl_add_u64 v[66:67], v[62:63], 0, v[0:1]
	global_load_dwordx4 v[62:65], v[66:67], off nt
	global_load_dwordx4 v[84:87], v[66:67], off offset:16 nt
	v_cmp_lt_i32_e32 vcc, s59, v61
	v_or_b32_e32 v89, 4, v90
	v_mov_b32_e32 v0, s31
	v_mov_b32_e32 v66, s31
	v_add_u32_e32 v67, 0x200, v61
	v_or_b32_e32 v91, 5, v90
	v_or_b32_e32 v93, 6, v90
	v_mul_lo_u32 v96, v88, s58
	v_lshlrev_b32_e32 v97, 1, v90
	s_or_b64 s[50:51], vcc, s[50:51]
	v_cmp_gt_i32_e32 vcc, v89, v88
	v_cmp_gt_i32_e64 s[12:13], v90, v88
	v_or_b32_e32 v92, 2, v90
	v_mov_b32_e32 v61, v67
	v_add3_u32 v67, s57, v96, v97
	v_cmp_lt_i32_e64 s[16:17], v90, v88
	v_or_b32_e32 v94, 3, v90
	v_or_b32_e32 v95, 7, v90
	v_add_u32_e32 v60, 0x1000, v60
	v_cmp_le_i32_e64 s[14:15], v95, v88
	s_waitcnt vmcnt(1)
	v_cndmask_b32_e64 v89, v64, v64, s[12:13]
	v_cndmask_b32_e64 v96, v65, v65, s[12:13]
	v_cndmask_b32_e64 v0, v62, v0, s[12:13]
	s_waitcnt vmcnt(0)
	v_cndmask_b32_e32 v66, v84, v66, vcc
	v_cndmask_b32_e32 v84, v87, v87, vcc
	v_cndmask_b32_e32 v86, v86, v86, vcc
	v_cndmask_b32_e32 v85, v85, v85, vcc
	v_cmp_le_i32_e32 vcc, v91, v88
	v_cmp_le_i32_e64 s[12:13], v93, v88
	v_cndmask_b32_e64 v0, v0, v62, s[16:17]
	v_cndmask_b32_e64 v62, v96, v65, s[16:17]
	v_cndmask_b32_e64 v64, v89, v64, s[16:17]
	v_cndmask_b32_e32 v65, 0, v85, vcc
	v_cndmask_b32_e64 v85, 0, v86, s[12:13]
	v_cmp_le_i32_e64 s[12:13], v92, v88
	v_cndmask_b32_e64 v63, 0, v63, s[16:17]
	v_cmp_le_i32_e32 vcc, v94, v88
	v_cndmask_b32_e64 v64, 0, v64, s[12:13]
	v_cndmask_b32_e64 v84, 0, v84, s[14:15]
	v_cndmask_b32_e32 v86, 0, v62, vcc
	v_cvt_pk_bf16_f32 v62, v0, v63
	v_cvt_pk_bf16_f32 v63, v64, v86
	v_cvt_pk_bf16_f32 v64, v66, v65
	v_cvt_pk_bf16_f32 v65, v85, v84
	ds_write_b128 v67, v[62:65]
	s_andn2_b64 exec, exec, s[50:51]
	s_cbranch_execnz .LBB0_361
.LBB0_362:
	s_or_b64 exec, exec, s[48:49]
	v_lshlrev_b32_e32 v0, 2, v137
	v_lshl_or_b32 v0, s61, 10, v0
	global_load_dwordx4 v[60:63], v0, s[20:21] nt
	global_load_dwordx4 v[64:67], v0, s[20:21] offset:16 nt
	s_mov_b32 s16, s61

.LBB0_365:
	s_or_b64 exec, exec, s[12:13]
	s_waitcnt lgkmcnt(0)
	s_barrier
	ds_read_b32 v0, v140
	s_waitcnt vmcnt(0)
	v_lshlrev_b32_e32 v84, 16, v24
	v_and_b32_e32 v85, 0xffff0000, v24
	s_add_i32 s17, s60, s42
	s_cmpk_gt_i32 s17, 0x7ff
	s_waitcnt lgkmcnt(0)
	v_mul_f32_e32 v84, v0, v84
	v_mul_f32_e32 v84, v60, v84
	v_mul_f32_e32 v85, v0, v85
	v_mul_f32_e32 v85, v61, v85
	v_cvt_pk_bf16_f32 v84, v84, v85
	ds_write_b32 v150, v84
	v_lshlrev_b32_e32 v84, 16, v25
	v_mul_f32_e32 v84, v0, v84
	v_and_b32_e32 v85, 0xffff0000, v25
	v_mul_f32_e32 v84, v62, v84
	v_mul_f32_e32 v85, v0, v85
	v_mul_f32_e32 v85, v63, v85
	v_cvt_pk_bf16_f32 v84, v84, v85
	ds_write_b32 v150, v84 offset:4
	v_lshlrev_b32_e32 v84, 16, v26
	v_mul_f32_e32 v84, v0, v84
	v_and_b32_e32 v85, 0xffff0000, v26
	v_mul_f32_e32 v84, v64, v84
	v_mul_f32_e32 v85, v0, v85
	v_mul_f32_e32 v85, v65, v85
	v_cvt_pk_bf16_f32 v84, v84, v85
	ds_write_b32 v150, v84 offset:8
	v_lshlrev_b32_e32 v84, 16, v27
	v_and_b32_e32 v85, 0xffff0000, v27
	v_mul_f32_e32 v84, v0, v84
	v_mul_f32_e32 v0, v0, v85
	v_mul_f32_e32 v84, v66, v84
	v_mul_f32_e32 v0, v67, v0
	v_cvt_pk_bf16_f32 v0, v84, v0
	ds_read_b32 v84, v141
	ds_write_b32 v150, v0 offset:12
	v_lshlrev_b32_e32 v0, 16, v32
	v_and_b32_e32 v85, 0xffff0000, v32
	s_cselect_b64 s[12:13], -1, 0
	s_waitcnt lgkmcnt(1)
	v_mul_f32_e32 v0, v84, v0
	v_mul_f32_e32 v0, v60, v0
	v_mul_f32_e32 v85, v84, v85
	v_mul_f32_e32 v85, v61, v85
	v_cvt_pk_bf16_f32 v0, v0, v85
	ds_write_b32 v150, v0 offset:8256
	v_lshlrev_b32_e32 v0, 16, v33
	v_mul_f32_e32 v0, v84, v0
	v_and_b32_e32 v85, 0xffff0000, v33
	v_mul_f32_e32 v0, v62, v0
	v_mul_f32_e32 v85, v84, v85
	v_mul_f32_e32 v85, v63, v85
	v_cvt_pk_bf16_f32 v0, v0, v85
	ds_write_b32 v150, v0 offset:8260
	v_lshlrev_b32_e32 v0, 16, v34
	v_mul_f32_e32 v0, v84, v0
	v_and_b32_e32 v85, 0xffff0000, v34
	v_mul_f32_e32 v0, v64, v0
	v_mul_f32_e32 v85, v84, v85
	v_mul_f32_e32 v85, v65, v85
	v_cvt_pk_bf16_f32 v0, v0, v85
	ds_write_b32 v150, v0 offset:8264
	v_lshlrev_b32_e32 v0, 16, v35
	v_and_b32_e32 v85, 0xffff0000, v35
	v_mul_f32_e32 v0, v84, v0
	v_mul_f32_e32 v84, v84, v85
	v_mul_f32_e32 v0, v66, v0
	v_mul_f32_e32 v84, v67, v84
	v_cvt_pk_bf16_f32 v0, v0, v84
	ds_read_b32 v84, v142
	ds_write_b32 v150, v0 offset:8268
	v_lshlrev_b32_e32 v0, 16, v44
	v_and_b32_e32 v85, 0xffff0000, v44
	s_and_b64 vcc, exec, s[12:13]
	s_waitcnt lgkmcnt(1)
	v_mul_f32_e32 v0, v84, v0
	v_mul_f32_e32 v0, v60, v0
	v_mul_f32_e32 v85, v84, v85
	v_mul_f32_e32 v85, v61, v85
	v_cvt_pk_bf16_f32 v0, v0, v85
	ds_write_b32 v150, v0 offset:16512
	v_lshlrev_b32_e32 v0, 16, v45
	v_mul_f32_e32 v0, v84, v0
	v_and_b32_e32 v85, 0xffff0000, v45
	v_mul_f32_e32 v0, v62, v0
	v_mul_f32_e32 v85, v84, v85
	v_mul_f32_e32 v85, v63, v85
	v_cvt_pk_bf16_f32 v0, v0, v85
	ds_write_b32 v150, v0 offset:16516
	v_lshlrev_b32_e32 v0, 16, v46
	v_mul_f32_e32 v0, v84, v0
	v_and_b32_e32 v85, 0xffff0000, v46
	v_mul_f32_e32 v0, v64, v0
	v_mul_f32_e32 v85, v84, v85
	v_mul_f32_e32 v85, v65, v85
	v_cvt_pk_bf16_f32 v0, v0, v85
	ds_write_b32 v150, v0 offset:16520
	v_lshlrev_b32_e32 v0, 16, v47
	v_and_b32_e32 v85, 0xffff0000, v47
	v_mul_f32_e32 v0, v84, v0
	v_mul_f32_e32 v84, v84, v85
	v_mul_f32_e32 v0, v66, v0
	v_mul_f32_e32 v84, v67, v84
	v_cvt_pk_bf16_f32 v0, v0, v84
	ds_read_b32 v84, v143
	ds_write_b32 v150, v0 offset:16524
	v_lshlrev_b32_e32 v0, 16, v28
	v_and_b32_e32 v85, 0xffff0000, v28
	s_waitcnt lgkmcnt(1)
	v_mul_f32_e32 v0, v84, v0
	v_mul_f32_e32 v0, v60, v0
	v_mul_f32_e32 v85, v84, v85
	v_mul_f32_e32 v85, v61, v85
	v_cvt_pk_bf16_f32 v0, v0, v85
	ds_write_b32 v150, v0 offset:24768
	v_lshlrev_b32_e32 v0, 16, v29
	v_mul_f32_e32 v0, v84, v0
	v_and_b32_e32 v85, 0xffff0000, v29
	v_mul_f32_e32 v0, v62, v0
	v_mul_f32_e32 v85, v84, v85
	v_mul_f32_e32 v85, v63, v85
	v_cvt_pk_bf16_f32 v0, v0, v85
	ds_write_b32 v150, v0 offset:24772
	v_lshlrev_b32_e32 v0, 16, v30
	v_mul_f32_e32 v0, v84, v0
	v_and_b32_e32 v85, 0xffff0000, v30
	v_mul_f32_e32 v0, v64, v0
	v_mul_f32_e32 v85, v84, v85
	v_mul_f32_e32 v85, v65, v85
	v_cvt_pk_bf16_f32 v0, v0, v85
	ds_write_b32 v150, v0 offset:24776
	v_lshlrev_b32_e32 v0, 16, v31
	v_and_b32_e32 v85, 0xffff0000, v31
	v_mul_f32_e32 v0, v84, v0
	v_mul_f32_e32 v84, v84, v85
	v_mul_f32_e32 v0, v66, v0
	v_mul_f32_e32 v84, v67, v84
	v_cvt_pk_bf16_f32 v0, v0, v84
	ds_read_b32 v84, v144
	ds_write_b32 v150, v0 offset:24780
	v_lshlrev_b32_e32 v0, 16, v40
	v_and_b32_e32 v85, 0xffff0000, v40
	s_waitcnt lgkmcnt(1)
	v_mul_f32_e32 v0, v84, v0
	v_mul_f32_e32 v0, v60, v0
	v_mul_f32_e32 v85, v84, v85
	v_mul_f32_e32 v85, v61, v85
	v_cvt_pk_bf16_f32 v0, v0, v85
	ds_write_b32 v150, v0 offset:33024
	v_lshlrev_b32_e32 v0, 16, v41
	v_mul_f32_e32 v0, v84, v0
	v_and_b32_e32 v85, 0xffff0000, v41
	v_mul_f32_e32 v0, v62, v0
	v_mul_f32_e32 v85, v84, v85
	v_mul_f32_e32 v85, v63, v85
	v_cvt_pk_bf16_f32 v0, v0, v85
	ds_write_b32 v150, v0 offset:33028
	v_lshlrev_b32_e32 v0, 16, v42
	v_mul_f32_e32 v0, v84, v0
	v_and_b32_e32 v85, 0xffff0000, v42
	v_mul_f32_e32 v0, v64, v0
	v_mul_f32_e32 v85, v84, v85
	v_mul_f32_e32 v85, v65, v85
	v_cvt_pk_bf16_f32 v0, v0, v85
	ds_write_b32 v150, v0 offset:33032
	v_lshlrev_b32_e32 v0, 16, v43
	v_and_b32_e32 v85, 0xffff0000, v43
	v_mul_f32_e32 v0, v84, v0
	v_mul_f32_e32 v84, v84, v85
	v_mul_f32_e32 v0, v66, v0
	v_mul_f32_e32 v84, v67, v84
	v_cvt_pk_bf16_f32 v0, v0, v84
	ds_read_b32 v84, v145
	ds_write_b32 v150, v0 offset:33036
	v_lshlrev_b32_e32 v0, 16, v20
	v_and_b32_e32 v85, 0xffff0000, v20
	s_waitcnt lgkmcnt(1)
	v_mul_f32_e32 v0, v84, v0
	v_mul_f32_e32 v0, v60, v0
	v_mul_f32_e32 v85, v84, v85
	v_mul_f32_e32 v85, v61, v85
	v_cvt_pk_bf16_f32 v0, v0, v85
	ds_write_b32 v150, v0 offset:41280
	v_lshlrev_b32_e32 v0, 16, v21
	v_mul_f32_e32 v0, v84, v0
	v_and_b32_e32 v85, 0xffff0000, v21
	v_mul_f32_e32 v0, v62, v0
	v_mul_f32_e32 v85, v84, v85
	v_mul_f32_e32 v85, v63, v85
	v_cvt_pk_bf16_f32 v0, v0, v85
	ds_write_b32 v150, v0 offset:41284
	v_lshlrev_b32_e32 v0, 16, v22
	v_mul_f32_e32 v0, v84, v0
	v_and_b32_e32 v85, 0xffff0000, v22
	v_mul_f32_e32 v0, v64, v0
	v_mul_f32_e32 v85, v84, v85
	v_mul_f32_e32 v85, v65, v85
	v_cvt_pk_bf16_f32 v0, v0, v85
	ds_write_b32 v150, v0 offset:41288
	v_lshlrev_b32_e32 v0, 16, v23
	v_and_b32_e32 v85, 0xffff0000, v23
	v_mul_f32_e32 v0, v84, v0
	v_mul_f32_e32 v84, v84, v85
	v_mul_f32_e32 v0, v66, v0
	v_mul_f32_e32 v84, v67, v84
	v_cvt_pk_bf16_f32 v0, v0, v84
	ds_read_b32 v84, v146
	ds_write_b32 v150, v0 offset:41292
	v_lshlrev_b32_e32 v0, 16, v36
	v_and_b32_e32 v85, 0xffff0000, v36
	s_waitcnt lgkmcnt(1)
	v_mul_f32_e32 v0, v84, v0
	v_mul_f32_e32 v0, v60, v0
	v_mul_f32_e32 v85, v84, v85
	v_mul_f32_e32 v85, v61, v85
	v_cvt_pk_bf16_f32 v0, v0, v85
	ds_write_b32 v150, v0 offset:49536
	v_lshlrev_b32_e32 v0, 16, v37
	v_mul_f32_e32 v0, v84, v0
	v_and_b32_e32 v85, 0xffff0000, v37
	v_mul_f32_e32 v0, v62, v0
	v_mul_f32_e32 v85, v84, v85
	v_mul_f32_e32 v85, v63, v85
	v_cvt_pk_bf16_f32 v0, v0, v85
	ds_write_b32 v150, v0 offset:49540
	v_lshlrev_b32_e32 v0, 16, v38
	v_mul_f32_e32 v0, v84, v0
	v_and_b32_e32 v85, 0xffff0000, v38
	v_mul_f32_e32 v0, v64, v0
	v_mul_f32_e32 v85, v84, v85
	v_mul_f32_e32 v85, v65, v85
	v_cvt_pk_bf16_f32 v0, v0, v85
	ds_write_b32 v150, v0 offset:49544
	v_lshlrev_b32_e32 v0, 16, v39
	v_and_b32_e32 v85, 0xffff0000, v39
	v_mul_f32_e32 v0, v84, v0
	v_mul_f32_e32 v84, v84, v85
	v_mul_f32_e32 v0, v66, v0
	v_mul_f32_e32 v84, v67, v84
	v_cvt_pk_bf16_f32 v0, v0, v84
	ds_read_b32 v84, v147
	ds_write_b32 v150, v0 offset:49548
	v_lshlrev_b32_e32 v0, 16, v52
	v_and_b32_e32 v85, 0xffff0000, v52
	s_waitcnt lgkmcnt(1)
	v_mul_f32_e32 v0, v84, v0
	v_mul_f32_e32 v0, v60, v0
	v_mul_f32_e32 v85, v84, v85
	v_mul_f32_e32 v85, v61, v85
	v_cvt_pk_bf16_f32 v0, v0, v85
	ds_write_b32 v150, v0 offset:57792
	v_lshlrev_b32_e32 v0, 16, v53
	v_mul_f32_e32 v0, v84, v0
	v_and_b32_e32 v85, 0xffff0000, v53
	v_mul_f32_e32 v0, v62, v0
	v_mul_f32_e32 v85, v84, v85
	v_mul_f32_e32 v85, v63, v85
	v_cvt_pk_bf16_f32 v0, v0, v85
	ds_write_b32 v150, v0 offset:57796
	v_lshlrev_b32_e32 v0, 16, v54
	v_mul_f32_e32 v0, v84, v0
	v_and_b32_e32 v85, 0xffff0000, v54
	v_mul_f32_e32 v0, v64, v0
	v_mul_f32_e32 v85, v84, v85
	v_mul_f32_e32 v85, v65, v85
	v_cvt_pk_bf16_f32 v0, v0, v85
	ds_write_b32 v150, v0 offset:57800
	v_lshlrev_b32_e32 v0, 16, v55
	v_mul_f32_e32 v0, v84, v0
	v_and_b32_e32 v85, 0xffff0000, v55
	v_mul_f32_e32 v0, v66, v0
	v_mul_f32_e32 v84, v84, v85
	v_mul_f32_e32 v84, v67, v84
	v_cvt_pk_bf16_f32 v0, v0, v84
	ds_write_b32 v150, v0 offset:57804
	s_waitcnt lgkmcnt(0)
	s_barrier
	s_cbranch_vccnz .LBB0_368
	s_lshl_b32 s14, s17, 4
	s_and_b32 s48, s14, 0xffffff80
	s_and_saveexec_b64 s[14:15], s[8:9]
	s_cbranch_execz .LBB0_354
	v_add_u32_e32 v4, s48, v134
	v_ashrrev_i32_e32 v5, 31, v4
	v_lshlrev_b64 v[4:5], 5, v[4:5]
	v_lshl_add_u64 v[8:9], s[28:29], 0, v[4:5]
	global_load_dwordx4 v[4:7], v[8:9], off offset:16 nt
	s_nop 0
	global_load_dwordx4 v[8:11], v[8:9], off nt
	s_branch .LBB0_354

.LBB0_937:
	v_ashrrev_i32_e32 v2, 2, v184
	v_and_b32_e32 v0, 0xffffffe0, v2
	v_ashrrev_i32_e32 v1, 31, v0
	v_and_b32_e32 v118, 0x7e0, v2
	v_lshlrev_b64 v[36:37], 11, v[0:1]
	v_cmp_eq_u32_e32 vcc, 0, v118
	v_min_u32_e32 v2, 2, v118
	v_lshl_add_u64 v[32:33], v[28:29], 0, v[36:37]
	v_cndmask_b32_e64 v1, -1, 0, vcc
	v_cndmask_b32_e64 v0, v117, 0, vcc
	v_lshlrev_b32_e32 v2, 11, v2
	v_lshl_add_u64 v[0:1], v[32:33], 0, v[0:1]
	v_sub_co_u32_e64 v2, s[14:15], v32, v2
	v_cndmask_b32_e64 v34, 1.0, 0, vcc
	s_nop 0
	v_subbrev_co_u32_e64 v3, s[14:15], 0, v33, s[14:15]
	global_load_dwordx4 v[40:43], v[0:1], off nt
	global_load_dwordx4 v[44:47], v[2:3], off nt
	v_min_u32_e32 v0, 3, v118
	v_lshlrev_b32_e32 v0, 11, v0
	v_sub_co_u32_e64 v0, s[14:15], v32, v0
	v_min_u32_e32 v2, 4, v118
	s_nop 0
	v_subbrev_co_u32_e64 v1, s[14:15], 0, v33, s[14:15]
	v_lshlrev_b32_e32 v2, 11, v2
	v_sub_co_u32_e64 v2, s[14:15], v32, v2
	v_sub_co_u32_e32 v119, vcc, 0, v118
	s_nop 0
	v_subbrev_co_u32_e64 v3, s[14:15], 0, v33, s[14:15]
	global_load_dwordx4 v[48:51], v[0:1], off nt
	global_load_dwordx4 v[52:55], v[2:3], off nt
	v_min_u32_e32 v0, 5, v118
	v_lshlrev_b32_e32 v0, 11, v0
	v_sub_co_u32_e64 v0, s[14:15], v32, v0
	v_min_u32_e32 v2, 6, v118
	s_nop 0
	v_subbrev_co_u32_e64 v1, s[14:15], 0, v33, s[14:15]
	v_lshlrev_b32_e32 v2, 11, v2
	v_sub_co_u32_e64 v2, s[14:15], v32, v2
	s_mov_b32 s53, -8
	s_nop 0
	v_subbrev_co_u32_e64 v3, s[14:15], 0, v33, s[14:15]
	global_load_dwordx4 v[56:59], v[0:1], off nt
	global_load_dwordx4 v[60:63], v[2:3], off nt
	v_min_u32_e32 v0, 7, v118
	v_lshlrev_b32_e32 v0, 11, v0
	v_sub_co_u32_e64 v0, s[14:15], v32, v0
	v_min_u32_e32 v2, 8, v118
	s_nop 0
	v_subbrev_co_u32_e64 v1, s[14:15], 0, v33, s[14:15]
	v_lshlrev_b32_e32 v2, 11, v2
	v_sub_co_u32_e64 v2, s[14:15], v32, v2
	s_waitcnt vmcnt(5)
	v_lshlrev_b32_e32 v74, 16, v40
	v_subbrev_co_u32_e64 v3, s[14:15], 0, v33, s[14:15]
	global_load_dwordx4 v[64:67], v[0:1], off nt
	global_load_dwordx4 v[68:71], v[2:3], off nt
	v_min_u32_e32 v0, 9, v118
	v_lshlrev_b32_e32 v0, 11, v0
	v_sub_co_u32_e64 v8, s[14:15], v32, v0
	v_min_u32_e32 v0, 10, v118
	s_nop 0
	v_subbrev_co_u32_e64 v9, s[14:15], 0, v33, s[14:15]
	v_lshlrev_b32_e32 v0, 11, v0
	v_sub_co_u32_e64 v10, s[14:15], v32, v0
	v_and_b32_e32 v75, 0xffff0000, v40
	s_nop 0
	v_subbrev_co_u32_e64 v11, s[14:15], 0, v33, s[14:15]
	global_load_dwordx4 v[4:7], v[8:9], off nt
	global_load_dwordx4 v[0:3], v[10:11], off nt
	v_min_u32_e32 v8, 11, v118
	v_lshlrev_b32_e32 v8, 11, v8
	v_sub_co_u32_e64 v16, s[14:15], v32, v8
	v_min_u32_e32 v8, 12, v118
	s_nop 0
	v_subbrev_co_u32_e64 v17, s[14:15], 0, v33, s[14:15]
	v_lshlrev_b32_e32 v8, 11, v8
	v_sub_co_u32_e64 v18, s[14:15], v32, v8
	v_lshlrev_b32_e32 v40, 16, v41
	s_nop 0
	v_subbrev_co_u32_e64 v19, s[14:15], 0, v33, s[14:15]
	global_load_dwordx4 v[12:15], v[16:17], off nt
	global_load_dwordx4 v[8:11], v[18:19], off nt
	v_min_u32_e32 v16, 13, v118
	v_lshlrev_b32_e32 v16, 11, v16
	v_sub_co_u32_e64 v24, s[14:15], v32, v16
	v_min_u32_e32 v16, 14, v118
	s_nop 0
	v_subbrev_co_u32_e64 v25, s[14:15], 0, v33, s[14:15]
	v_lshlrev_b32_e32 v16, 11, v16
	v_sub_co_u32_e64 v26, s[14:15], v32, v16
	v_and_b32_e32 v41, 0xffff0000, v41
	s_nop 0
	v_subbrev_co_u32_e64 v27, s[14:15], 0, v33, s[14:15]
	global_load_dwordx4 v[20:23], v[24:25], off nt
	global_load_dwordx4 v[16:19], v[26:27], off nt
	v_min_u32_e32 v24, 15, v118
	v_lshlrev_b32_e32 v24, 11, v24
	v_sub_co_u32_e64 v24, s[14:15], v32, v24
	s_waitcnt vmcnt(12)
	v_lshlrev_b32_e32 v76, 16, v44
	v_subbrev_co_u32_e64 v25, s[14:15], 0, v33, s[14:15]
	global_load_dwordx4 v[24:27], v[24:25], off nt
	s_and_b64 s[14:15], s[6:7], vcc
	v_cndmask_b32_e64 v72, 0, 1.0, s[14:15]
	v_and_b32_e32 v77, 0xffff0000, v44
	v_pk_fma_f32 v[40:41], v[34:35], v[40:41], 0 op_sel_hi:[0,1,0]
	v_lshlrev_b32_e32 v44, 16, v45
	v_and_b32_e32 v45, 0xffff0000, v45
	s_and_b64 s[14:15], s[10:11], vcc
	v_pk_fma_f32 v[40:41], v[72:73], v[44:45], v[40:41] op_sel_hi:[0,1,1]
	s_waitcnt vmcnt(12)
	v_lshlrev_b32_e32 v44, 16, v49
	v_and_b32_e32 v45, 0xffff0000, v49
	v_cndmask_b32_e64 v38, 0, 1.0, s[14:15]
	v_pk_fma_f32 v[40:41], v[72:73], v[44:45], v[40:41] op_sel_hi:[0,1,1]
	s_waitcnt vmcnt(11)
	v_lshlrev_b32_e32 v44, 16, v53
	v_and_b32_e32 v45, 0xffff0000, v53
	v_pk_fma_f32 v[40:41], v[38:39], v[44:45], v[40:41] op_sel_hi:[0,1,1]
	v_lshlrev_b32_e32 v44, 16, v42
	v_and_b32_e32 v45, 0xffff0000, v42
	v_lshlrev_b32_e32 v42, 16, v43
	v_and_b32_e32 v43, 0xffff0000, v43
	v_pk_fma_f32 v[74:75], v[34:35], v[74:75], 0 op_sel_hi:[0,1,0]
	v_pk_fma_f32 v[44:45], v[34:35], v[44:45], 0 op_sel_hi:[0,1,0]
	v_pk_fma_f32 v[34:35], v[34:35], v[42:43], 0 op_sel_hi:[0,1,0]
	v_lshlrev_b32_e32 v42, 16, v47
	v_and_b32_e32 v43, 0xffff0000, v47
	v_pk_fma_f32 v[74:75], v[72:73], v[76:77], v[74:75] op_sel_hi:[0,1,1]
	v_lshlrev_b32_e32 v76, 16, v48
	v_and_b32_e32 v77, 0xffff0000, v48
	v_pk_fma_f32 v[34:35], v[72:73], v[42:43], v[34:35] op_sel_hi:[0,1,1]
	v_lshlrev_b32_e32 v42, 16, v51
	v_and_b32_e32 v43, 0xffff0000, v51
	v_pk_fma_f32 v[74:75], v[72:73], v[76:77], v[74:75] op_sel_hi:[0,1,1]
	v_lshlrev_b32_e32 v76, 16, v52
	v_and_b32_e32 v77, 0xffff0000, v52
	v_lshlrev_b32_e32 v48, 16, v46
	v_and_b32_e32 v49, 0xffff0000, v46
	v_pk_fma_f32 v[34:35], v[72:73], v[42:43], v[34:35] op_sel_hi:[0,1,1]
	v_lshlrev_b32_e32 v42, 16, v55
	v_and_b32_e32 v43, 0xffff0000, v55
	v_pk_fma_f32 v[74:75], v[38:39], v[76:77], v[74:75] op_sel_hi:[0,1,1]
	v_pk_fma_f32 v[44:45], v[72:73], v[48:49], v[44:45] op_sel_hi:[0,1,1]
	v_lshlrev_b32_e32 v48, 16, v50
	v_and_b32_e32 v49, 0xffff0000, v50
	v_pk_fma_f32 v[42:43], v[38:39], v[42:43], v[34:35] op_sel_hi:[0,1,1]
	s_waitcnt vmcnt(10)
	v_lshlrev_b32_e32 v34, 16, v56
	v_and_b32_e32 v35, 0xffff0000, v56
	v_lshlrev_b32_e32 v46, 16, v57
	v_and_b32_e32 v47, 0xffff0000, v57
	v_pk_fma_f32 v[44:45], v[72:73], v[48:49], v[44:45] op_sel_hi:[0,1,1]
	v_lshlrev_b32_e32 v48, 16, v54
	v_and_b32_e32 v49, 0xffff0000, v54
	s_waitcnt vmcnt(9)
	v_lshlrev_b32_e32 v52, 16, v60
	v_and_b32_e32 v53, 0xffff0000, v60
	v_lshlrev_b32_e32 v54, 16, v61
	v_and_b32_e32 v55, 0xffff0000, v61
	v_pk_fma_f32 v[34:35], v[38:39], v[34:35], v[74:75] op_sel_hi:[0,1,1]
	v_pk_fma_f32 v[40:41], v[38:39], v[46:47], v[40:41] op_sel_hi:[0,1,1]
	v_pk_fma_f32 v[44:45], v[38:39], v[48:49], v[44:45] op_sel_hi:[0,1,1]
	v_lshlrev_b32_e32 v48, 16, v58
	v_and_b32_e32 v49, 0xffff0000, v58
	v_lshlrev_b32_e32 v50, 16, v59
	v_and_b32_e32 v51, 0xffff0000, v59
	v_lshlrev_b32_e32 v56, 16, v62
	v_and_b32_e32 v57, 0xffff0000, v62
	v_lshlrev_b32_e32 v58, 16, v63
	v_and_b32_e32 v59, 0xffff0000, v63
	s_waitcnt vmcnt(8)
	v_lshlrev_b32_e32 v60, 16, v64
	v_and_b32_e32 v61, 0xffff0000, v64
	v_lshlrev_b32_e32 v62, 16, v65
	v_and_b32_e32 v63, 0xffff0000, v65
	s_and_b64 s[14:15], s[12:13], vcc
	v_pk_fma_f32 v[34:35], v[38:39], v[52:53], v[34:35] op_sel_hi:[0,1,1]
	v_pk_fma_f32 v[40:41], v[38:39], v[54:55], v[40:41] op_sel_hi:[0,1,1]
	v_cndmask_b32_e64 v72, 0, 1.0, s[14:15]
	s_waitcnt vmcnt(7)
	v_lshlrev_b32_e32 v76, 16, v68
	v_and_b32_e32 v77, 0xffff0000, v68
	v_lshlrev_b32_e32 v68, 16, v69
	v_and_b32_e32 v69, 0xffff0000, v69
	v_pk_fma_f32 v[34:35], v[38:39], v[60:61], v[34:35] op_sel_hi:[0,1,1]
	v_pk_fma_f32 v[40:41], v[38:39], v[62:63], v[40:41] op_sel_hi:[0,1,1]
	v_pk_fma_f32 v[34:35], v[72:73], v[76:77], v[34:35] op_sel_hi:[0,1,1]
	s_waitcnt vmcnt(6)
	v_lshlrev_b32_e32 v52, 16, v4
	v_and_b32_e32 v53, 0xffff0000, v4
	v_pk_fma_f32 v[40:41], v[72:73], v[68:69], v[40:41] op_sel_hi:[0,1,1]
	v_lshlrev_b32_e32 v4, 16, v5
	v_and_b32_e32 v5, 0xffff0000, v5
	v_pk_fma_f32 v[34:35], v[72:73], v[52:53], v[34:35] op_sel_hi:[0,1,1]
	s_waitcnt vmcnt(5)
	v_lshlrev_b32_e32 v52, 16, v0
	v_and_b32_e32 v53, 0xffff0000, v0
	v_pk_fma_f32 v[4:5], v[72:73], v[4:5], v[40:41] op_sel_hi:[0,1,1]
	v_lshlrev_b32_e32 v0, 16, v1
	v_and_b32_e32 v1, 0xffff0000, v1
	v_pk_fma_f32 v[0:1], v[72:73], v[0:1], v[4:5] op_sel_hi:[0,1,1]
	s_waitcnt vmcnt(4)
	v_lshlrev_b32_e32 v4, 16, v13
	v_and_b32_e32 v5, 0xffff0000, v13
	v_pk_fma_f32 v[0:1], v[72:73], v[4:5], v[0:1] op_sel_hi:[0,1,1]
	s_waitcnt vmcnt(3)
	v_lshlrev_b32_e32 v4, 16, v9
	v_and_b32_e32 v5, 0xffff0000, v9
	v_pk_fma_f32 v[0:1], v[72:73], v[4:5], v[0:1] op_sel_hi:[0,1,1]
	s_waitcnt vmcnt(2)
	v_lshlrev_b32_e32 v4, 16, v21
	v_and_b32_e32 v5, 0xffff0000, v21
	v_pk_fma_f32 v[0:1], v[72:73], v[4:5], v[0:1] op_sel_hi:[0,1,1]
	s_waitcnt vmcnt(1)
	v_lshlrev_b32_e32 v4, 16, v17
	v_and_b32_e32 v5, 0xffff0000, v17
	v_pk_fma_f32 v[0:1], v[72:73], v[4:5], v[0:1] op_sel_hi:[0,1,1]
	s_waitcnt vmcnt(0)
	v_lshlrev_b32_e32 v4, 16, v25
	v_and_b32_e32 v5, 0xffff0000, v25
	v_pk_fma_f32 v[4:5], v[72:73], v[4:5], v[0:1] op_sel_hi:[0,1,1]
	v_pk_fma_f32 v[0:1], v[38:39], v[48:49], v[44:45] op_sel_hi:[0,1,1]
	v_lshlrev_b32_e32 v64, 16, v66
	v_and_b32_e32 v65, 0xffff0000, v66
	v_pk_fma_f32 v[0:1], v[38:39], v[56:57], v[0:1] op_sel_hi:[0,1,1]
	v_lshlrev_b32_e32 v78, 16, v70
	v_and_b32_e32 v79, 0xffff0000, v70
	v_pk_fma_f32 v[34:35], v[72:73], v[52:53], v[34:35] op_sel_hi:[0,1,1]
	v_lshlrev_b32_e32 v52, 16, v12
	v_and_b32_e32 v53, 0xffff0000, v12
	v_pk_fma_f32 v[0:1], v[38:39], v[64:65], v[0:1] op_sel_hi:[0,1,1]
	v_pk_fma_f32 v[34:35], v[72:73], v[52:53], v[34:35] op_sel_hi:[0,1,1]
	v_lshlrev_b32_e32 v52, 16, v8
	v_and_b32_e32 v53, 0xffff0000, v8
	v_pk_fma_f32 v[0:1], v[72:73], v[78:79], v[0:1] op_sel_hi:[0,1,1]
	v_lshlrev_b32_e32 v8, 16, v6
	v_and_b32_e32 v9, 0xffff0000, v6
	v_pk_fma_f32 v[0:1], v[72:73], v[8:9], v[0:1] op_sel_hi:[0,1,1]
	v_lshlrev_b32_e32 v8, 16, v2
	v_and_b32_e32 v9, 0xffff0000, v2
	v_pk_fma_f32 v[0:1], v[72:73], v[8:9], v[0:1] op_sel_hi:[0,1,1]
	v_lshlrev_b32_e32 v8, 16, v14
	v_and_b32_e32 v9, 0xffff0000, v14
	v_pk_fma_f32 v[0:1], v[72:73], v[8:9], v[0:1] op_sel_hi:[0,1,1]
	v_lshlrev_b32_e32 v8, 16, v10
	v_and_b32_e32 v9, 0xffff0000, v10
	v_pk_fma_f32 v[0:1], v[72:73], v[8:9], v[0:1] op_sel_hi:[0,1,1]
	v_lshlrev_b32_e32 v8, 16, v22
	v_and_b32_e32 v9, 0xffff0000, v22
	v_pk_fma_f32 v[0:1], v[72:73], v[8:9], v[0:1] op_sel_hi:[0,1,1]
	v_lshlrev_b32_e32 v8, 16, v18
	v_and_b32_e32 v9, 0xffff0000, v18
	v_pk_fma_f32 v[0:1], v[72:73], v[8:9], v[0:1] op_sel_hi:[0,1,1]
	v_lshlrev_b32_e32 v8, 16, v26
	v_and_b32_e32 v9, 0xffff0000, v26
	v_pk_fma_f32 v[8:9], v[72:73], v[8:9], v[0:1] op_sel_hi:[0,1,1]
	v_pk_fma_f32 v[0:1], v[38:39], v[50:51], v[42:43] op_sel_hi:[0,1,1]
	v_lshlrev_b32_e32 v66, 16, v67
	v_and_b32_e32 v67, 0xffff0000, v67
	v_pk_fma_f32 v[0:1], v[38:39], v[58:59], v[0:1] op_sel_hi:[0,1,1]
	v_lshlrev_b32_e32 v70, 16, v71
	v_and_b32_e32 v71, 0xffff0000, v71
	v_pk_fma_f32 v[0:1], v[38:39], v[66:67], v[0:1] op_sel_hi:[0,1,1]
	v_pk_fma_f32 v[0:1], v[72:73], v[70:71], v[0:1] op_sel_hi:[0,1,1]
	v_lshlrev_b32_e32 v6, 16, v7
	v_and_b32_e32 v7, 0xffff0000, v7
	v_pk_fma_f32 v[0:1], v[72:73], v[6:7], v[0:1] op_sel_hi:[0,1,1]
	v_lshlrev_b32_e32 v2, 16, v3
	v_and_b32_e32 v3, 0xffff0000, v3
	v_pk_fma_f32 v[0:1], v[72:73], v[2:3], v[0:1] op_sel_hi:[0,1,1]
	v_lshlrev_b32_e32 v2, 16, v15
	v_and_b32_e32 v3, 0xffff0000, v15
	v_pk_fma_f32 v[0:1], v[72:73], v[2:3], v[0:1] op_sel_hi:[0,1,1]
	v_lshlrev_b32_e32 v2, 16, v11
	v_and_b32_e32 v3, 0xffff0000, v11
	v_pk_fma_f32 v[34:35], v[72:73], v[52:53], v[34:35] op_sel_hi:[0,1,1]
	v_lshlrev_b32_e32 v52, 16, v20
	v_and_b32_e32 v53, 0xffff0000, v20
	v_pk_fma_f32 v[0:1], v[72:73], v[2:3], v[0:1] op_sel_hi:[0,1,1]
	v_lshlrev_b32_e32 v2, 16, v23
	v_and_b32_e32 v3, 0xffff0000, v23
	v_pk_fma_f32 v[34:35], v[72:73], v[52:53], v[34:35] op_sel_hi:[0,1,1]
	v_lshlrev_b32_e32 v52, 16, v16
	v_and_b32_e32 v53, 0xffff0000, v16
	v_pk_fma_f32 v[0:1], v[72:73], v[2:3], v[0:1] op_sel_hi:[0,1,1]
	v_lshlrev_b32_e32 v2, 16, v19
	v_and_b32_e32 v3, 0xffff0000, v19
	v_pk_fma_f32 v[34:35], v[72:73], v[52:53], v[34:35] op_sel_hi:[0,1,1]
	v_lshlrev_b32_e32 v52, 16, v24
	v_and_b32_e32 v53, 0xffff0000, v24
	v_pk_fma_f32 v[0:1], v[72:73], v[2:3], v[0:1] op_sel_hi:[0,1,1]
	v_lshlrev_b32_e32 v2, 16, v27
	v_and_b32_e32 v3, 0xffff0000, v27
	v_pk_fma_f32 v[34:35], v[72:73], v[52:53], v[34:35] op_sel_hi:[0,1,1]
	v_pk_fma_f32 v[2:3], v[72:73], v[2:3], v[0:1] op_sel_hi:[0,1,1]
	v_lshl_add_u64 v[0:1], v[30:31], 0, v[36:37]
	v_mov_b32_e32 v6, v35
	v_mov_b32_e32 v10, v5
	v_mov_b32_e32 v12, v9
	v_mov_b32_e32 v14, v3
.LBB0_938:
	v_add_co_u32_e64 v22, s[14:15], s3, v0
	v_add_co_u32_e32 v20, vcc, 0xfbffd000, v0
	s_nop 0
	v_addc_co_u32_e64 v23, s[14:15], -1, v1, s[14:15]
	v_add_co_u32_e64 v24, s[14:15], s35, v0
	v_add_u32_e32 v5, s53, v118
	s_nop 0
	v_addc_co_u32_e64 v25, s[14:15], -1, v1, s[14:15]
	v_addc_co_u32_e32 v21, vcc, -1, v1, vcc
	global_load_dwordx4 v[38:41], v[22:23], off offset:-2048 nt
	global_load_dwordx4 v[42:45], v[24:25], off offset:-4096 nt
	global_load_dwordx4 v[46:49], v[24:25], off offset:-2048 nt
	global_load_dwordx4 v[50:53], v[24:25], off nt
	v_add_u32_e32 v25, 8, v5
	v_add_u32_e32 v3, s53, v116
	v_cmp_lt_u32_e32 vcc, v25, v114
	v_add_co_u32_e64 v26, s[14:15], s48, v0
	v_add_u32_e32 v23, 15, v3
	v_add_u32_e32 v57, 11, v5
	v_cndmask_b32_e64 v35, 1.0, 0, vcc
	v_cmp_lt_u32_e32 vcc, v25, v115
	v_addc_co_u32_e64 v27, s[14:15], -1, v1, s[14:15]
	v_add_u32_e32 v59, 12, v5
	v_max_i32_e32 v62, v23, v119
	v_cndmask_b32_e64 v23, 1.0, 0, vcc
	v_cmp_gt_u32_e32 vcc, v57, v115
	v_add_u32_e32 v7, 9, v3
	global_load_dwordx4 v[86:89], v[26:27], off offset:-2048 nt
	global_load_dwordx4 v[90:93], v[26:27], off nt
	v_add_u32_e32 v61, 13, v5
	global_load_dwordx4 v[94:97], v[20:21], off offset:-2048 nt
	global_load_dwordx4 v[120:123], v[20:21], off nt
	v_cndmask_b32_e64 v185, 0, 1.0, vcc
	v_cmp_lt_u32_e32 vcc, v59, v114
	v_add_u32_e32 v9, 10, v3
	v_add_u32_e32 v11, 11, v3
	v_add_u32_e32 v13, 12, v3
	v_add_u32_e32 v15, 13, v3
	v_add_u32_e32 v22, 14, v3
	v_add_u32_e32 v3, 16, v3
	v_add_u32_e32 v63, 14, v5
	v_max_i32_e32 v24, v7, v119
	v_cndmask_b32_e64 v207, 1.0, 0, vcc
	v_cmp_gt_u32_e32 vcc, v61, v115
	v_add_u32_e32 v27, 9, v5
	v_add_u32_e32 v55, 10, v5
	v_add_u32_e32 v65, 15, v5
	v_max_i32_e32 v26, v9, v119
	v_max_i32_e32 v54, v11, v119
	v_max_i32_e32 v56, v13, v119
	v_max_i32_e32 v58, v15, v119
	v_max_i32_e32 v60, v22, v119
	v_max_i32_e32 v64, v3, v119
	v_cndmask_b32_e64 v209, 0, 1.0, vcc
	v_cmp_lt_u32_e32 vcc, v63, v114
	v_ashrrev_i32_e32 v25, 31, v24
	v_min_u32_e32 v3, v27, v114
	v_min_u32_e32 v21, v55, v114
	v_min_u32_e32 v66, v57, v114
	v_min_u32_e32 v67, v59, v114
	v_min_u32_e32 v68, v61, v114
	v_min_u32_e32 v69, v63, v114
	v_min_u32_e32 v70, v65, v114
	v_cndmask_b32_e64 v22, 1.0, 0, vcc
	v_cmp_gt_u32_e32 vcc, v65, v115
	v_ashrrev_i32_e32 v27, 31, v26
	v_ashrrev_i32_e32 v55, 31, v54
	v_ashrrev_i32_e32 v57, 31, v56
	v_ashrrev_i32_e32 v59, 31, v58
	v_ashrrev_i32_e32 v61, 31, v60
	v_ashrrev_i32_e32 v63, 31, v62
	v_ashrrev_i32_e32 v65, 31, v64
	v_lshlrev_b64 v[24:25], 11, v[24:25]
	v_lshlrev_b64 v[26:27], 11, v[26:27]
	v_lshlrev_b64 v[54:55], 11, v[54:55]
	v_lshlrev_b64 v[56:57], 11, v[56:57]
	v_lshlrev_b64 v[58:59], 11, v[58:59]
	v_lshlrev_b64 v[60:61], 11, v[60:61]
	v_lshlrev_b64 v[62:63], 11, v[62:63]
	v_lshlrev_b64 v[64:65], 11, v[64:65]
	v_lshl_add_u64 v[24:25], v[32:33], 0, v[24:25]
	v_lshl_add_u64 v[26:27], v[32:33], 0, v[26:27]
	v_lshl_add_u64 v[54:55], v[32:33], 0, v[54:55]
	v_lshl_add_u64 v[56:57], v[32:33], 0, v[56:57]
	v_lshl_add_u64 v[58:59], v[32:33], 0, v[58:59]
	v_lshl_add_u64 v[60:61], v[32:33], 0, v[60:61]
	v_lshl_add_u64 v[62:63], v[32:33], 0, v[62:63]
	v_lshl_add_u64 v[64:65], v[32:33], 0, v[64:65]
	global_load_dwordx4 v[124:127], v[24:25], off nt
	global_load_dwordx4 v[128:131], v[26:27], off nt
	global_load_dwordx4 v[132:135], v[54:55], off nt
	global_load_dwordx4 v[136:139], v[56:57], off nt
	global_load_dwordx4 v[140:143], v[58:59], off nt
	global_load_dwordx4 v[144:147], v[60:61], off nt
	global_load_dwordx4 v[148:151], v[62:63], off nt
	global_load_dwordx4 v[152:155], v[64:65], off nt
	v_add_co_u32_e64 v16, s[14:15], s49, v0
	v_cvt_f32_ubyte0_e32 v72, v3
	s_nop 0
	v_addc_co_u32_e64 v17, s[14:15], -1, v1, s[14:15]
	v_add_co_u32_e64 v18, s[14:15], s50, v0
	v_cvt_f32_ubyte0_e32 v21, v21
	s_nop 0
	v_addc_co_u32_e64 v19, s[14:15], -1, v1, s[14:15]
	v_add_co_u32_e64 v36, s[14:15], s51, v0
	v_cvt_f32_ubyte0_e32 v66, v66
	s_nop 0
	v_addc_co_u32_e64 v37, s[14:15], -1, v1, s[14:15]
	v_div_scale_f32 v73, s[14:15], v72, v72, 1.0
	v_div_scale_f32 v75, s[14:15], v21, v21, 1.0
	v_rcp_f32_e32 v101, v73
	v_cvt_f32_ubyte0_e32 v67, v67
	v_div_scale_f32 v77, s[16:17], v66, v66, 1.0
	v_rcp_f32_e32 v102, v75
	v_cvt_f32_ubyte0_e32 v68, v68
	v_div_scale_f32 v79, s[20:21], v67, v67, 1.0
	v_rcp_f32_e32 v103, v77
	v_add_u32_e32 v5, 16, v5
	v_cvt_f32_ubyte0_e32 v69, v69
	v_div_scale_f32 v81, s[22:23], v68, v68, 1.0
	v_rcp_f32_e32 v104, v79
	v_min_u32_e32 v71, v5, v114
	v_cvt_f32_ubyte0_e32 v70, v70
	v_div_scale_f32 v83, s[24:25], v69, v69, 1.0
	v_rcp_f32_e32 v105, v81
	v_fma_f32 v24, -v73, v101, 1.0
	v_cndmask_b32_e64 v20, 0, 1.0, vcc
	v_cvt_f32_ubyte0_e32 v71, v71
	v_div_scale_f32 v74, vcc, 1.0, v72, 1.0
	v_div_scale_f32 v85, s[26:27], v70, v70, 1.0
	v_rcp_f32_e32 v106, v83
	v_fma_f32 v25, -v75, v102, 1.0
	v_fmac_f32_e32 v101, v24, v101
	v_div_scale_f32 v76, s[14:15], 1.0, v21, 1.0
	v_div_scale_f32 v99, s[28:29], v71, v71, 1.0
	v_rcp_f32_e32 v107, v85
	v_fma_f32 v26, -v77, v103, 1.0
	v_fmac_f32_e32 v102, v25, v102
	v_mul_f32_e32 v24, v74, v101
	v_div_scale_f32 v78, s[16:17], 1.0, v66, 1.0
	v_rcp_f32_e32 v108, v99
	v_fma_f32 v27, -v79, v104, 1.0
	v_fmac_f32_e32 v103, v26, v103
	v_mul_f32_e32 v25, v76, v102
	v_fma_f32 v58, -v73, v24, v74
	v_div_scale_f32 v80, s[20:21], 1.0, v67, 1.0
	v_fma_f32 v54, -v81, v105, 1.0
	v_fmac_f32_e32 v104, v27, v104
	v_mul_f32_e32 v26, v78, v103
	v_fma_f32 v59, -v75, v25, v76
	v_fmac_f32_e32 v24, v58, v101
	v_div_scale_f32 v82, s[22:23], 1.0, v68, 1.0
	v_fma_f32 v55, -v83, v106, 1.0
	v_fmac_f32_e32 v105, v54, v105
	v_mul_f32_e32 v27, v80, v104
	v_fma_f32 v60, -v77, v26, v78
	v_fmac_f32_e32 v25, v59, v102
	v_fma_f32 v58, -v73, v24, v74
	v_div_scale_f32 v84, s[24:25], 1.0, v69, 1.0
	v_fma_f32 v56, -v85, v107, 1.0
	v_fmac_f32_e32 v106, v55, v106
	v_mul_f32_e32 v54, v82, v105
	v_fma_f32 v61, -v79, v27, v80
	v_fmac_f32_e32 v26, v60, v103
	v_fma_f32 v59, -v75, v25, v76
	v_div_fmas_f32 v24, v58, v101, v24
	s_mov_b64 vcc, s[14:15]
	v_div_scale_f32 v98, s[26:27], 1.0, v70, 1.0
	v_fma_f32 v57, -v99, v108, 1.0
	v_fmac_f32_e32 v107, v56, v107
	v_mul_f32_e32 v55, v84, v106
	v_fma_f32 v62, -v81, v54, v82
	v_fmac_f32_e32 v27, v61, v104
	v_fma_f32 v60, -v77, v26, v78
	v_div_fixup_f32 v211, v24, v72, 1.0
	v_div_fmas_f32 v24, v59, v102, v25
	s_mov_b64 vcc, s[16:17]
	v_div_scale_f32 v100, s[28:29], 1.0, v71, 1.0
	v_fmac_f32_e32 v108, v57, v108
	v_mul_f32_e32 v56, v98, v107
	v_fma_f32 v63, -v83, v55, v84
	v_fmac_f32_e32 v54, v62, v105
	v_fma_f32 v61, -v79, v27, v80
	v_div_fixup_f32 v21, v24, v21, 1.0
	v_div_fmas_f32 v24, v60, v103, v26
	s_mov_b64 vcc, s[20:21]
	v_mov_b32_e32 v7, v35
	v_mov_b32_e32 v5, v35
	v_mul_f32_e32 v57, v100, v108
	v_fma_f32 v64, -v85, v56, v98
	v_fmac_f32_e32 v55, v63, v106
	v_fma_f32 v62, -v81, v54, v82
	v_div_fixup_f32 v213, v24, v66, 1.0
	v_div_fmas_f32 v24, v61, v104, v27
	s_mov_b64 vcc, s[22:23]
	s_waitcnt vmcnt(9)
	v_lshlrev_b32_e32 v176, 16, v94
	v_and_b32_e32 v178, 0xffff0000, v94
	v_lshlrev_b32_e32 v180, 16, v95
	s_waitcnt vmcnt(7)
	v_lshlrev_b32_e32 v177, 16, v124
	v_and_b32_e32 v179, 0xffff0000, v124
	v_lshlrev_b32_e32 v181, 16, v125
	v_mov_b32_e32 v11, v35
	v_mov_b32_e32 v9, v35
	v_mov_b32_e32 v13, v35
	v_fma_f32 v65, -v99, v57, v100
	v_fmac_f32_e32 v56, v64, v107
	v_fma_f32 v63, -v83, v55, v84
	v_div_fixup_f32 v215, v24, v67, 1.0
	v_div_fmas_f32 v24, v62, v105, v54
	s_mov_b64 vcc, s[24:25]
	v_and_b32_e32 v182, 0xffff0000, v95
	v_lshlrev_b32_e32 v186, 16, v96
	v_and_b32_e32 v188, 0xffff0000, v96
	v_and_b32_e32 v183, 0xffff0000, v125
	v_lshlrev_b32_e32 v187, 16, v126
	v_and_b32_e32 v189, 0xffff0000, v126
	v_pk_add_f32 v[124:125], v[34:35], v[176:177]
	v_pk_add_f32 v[6:7], v[6:7], v[178:179]
	v_pk_add_f32 v[4:5], v[4:5], v[180:181]
	v_mov_b32_e32 v3, v35
	v_mov_b32_e32 v15, v35
	v_fmac_f32_e32 v57, v65, v108
	v_fma_f32 v64, -v85, v56, v98
	v_div_fixup_f32 v217, v24, v68, 1.0
	v_div_fmas_f32 v24, v63, v106, v55
	s_mov_b64 vcc, s[26:27]
	v_lshlrev_b32_e32 v190, 16, v97
	v_and_b32_e32 v192, 0xffff0000, v97
	v_lshlrev_b32_e32 v196, 16, v121
	v_and_b32_e32 v198, 0xffff0000, v121
	v_lshlrev_b32_e32 v202, 16, v123
	v_and_b32_e32 v204, 0xffff0000, v123
	v_lshlrev_b32_e32 v191, 16, v127
	v_and_b32_e32 v193, 0xffff0000, v127
	s_waitcnt vmcnt(6)
	v_lshlrev_b32_e32 v195, 16, v128
	v_and_b32_e32 v121, 0xffff0000, v128
	v_lshlrev_b32_e32 v201, 16, v130
	v_and_b32_e32 v123, 0xffff0000, v130
	v_lshlrev_b32_e32 v203, 16, v131
	v_and_b32_e32 v205, 0xffff0000, v131
	s_waitcnt vmcnt(5)
	v_lshlrev_b32_e32 v161, 16, v132
	v_and_b32_e32 v163, 0xffff0000, v132
	v_lshlrev_b32_e32 v165, 16, v133
	v_and_b32_e32 v167, 0xffff0000, v133
	v_lshlrev_b32_e32 v169, 16, v134
	v_and_b32_e32 v171, 0xffff0000, v134
	v_lshlrev_b32_e32 v173, 16, v135
	v_and_b32_e32 v175, 0xffff0000, v135
	v_pk_add_f32 v[10:11], v[10:11], v[182:183]
	v_pk_add_f32 v[8:9], v[8:9], v[186:187]
	v_pk_add_f32 v[12:13], v[12:13], v[188:189]
	v_mul_f32_e32 v34, v35, v177
	v_mul_f32_e32 v126, v35, v179
	v_mul_f32_e32 v128, v35, v181
	v_mul_f32_e32 v130, v35, v183
	v_mul_f32_e32 v132, v35, v187
	v_mul_f32_e32 v134, v35, v189
	v_fma_f32 v131, v211, v124, -v176
	v_fma_f32 v133, v211, v6, -v178
	v_fma_f32 v135, v211, v4, -v180
	v_fma_f32 v65, -v99, v57, v100
	v_div_fixup_f32 v219, v24, v69, 1.0
	v_div_fmas_f32 v24, v64, v107, v56
	s_mov_b64 vcc, s[28:29]
	s_waitcnt vmcnt(4)
	v_lshlrev_b32_e32 v113, 16, v136
	v_and_b32_e32 v99, 0xffff0000, v136
	v_lshlrev_b32_e32 v111, 16, v137
	v_and_b32_e32 v101, 0xffff0000, v137
	v_lshlrev_b32_e32 v109, 16, v138
	v_and_b32_e32 v103, 0xffff0000, v138
	v_lshlrev_b32_e32 v107, 16, v139
	v_and_b32_e32 v105, 0xffff0000, v139
	s_waitcnt vmcnt(3)
	v_lshlrev_b32_e32 v83, 16, v141
	v_and_b32_e32 v73, 0xffff0000, v141
	v_pk_add_f32 v[2:3], v[2:3], v[190:191]
	v_pk_add_f32 v[14:15], v[14:15], v[192:193]
	v_mul_f32_e32 v136, v35, v191
	v_mul_f32_e32 v138, v35, v193
	v_fma_f32 v137, v211, v10, -v182
	v_fma_f32 v139, v211, v8, -v186
	v_fma_f32 v141, v211, v12, -v188
	v_pk_add_f32 v[34:35], v[124:125], v[34:35] op_sel_hi:[1,0] neg_lo:[0,1] neg_hi:[0,1]
	v_pk_add_f32 v[6:7], v[6:7], v[126:127] op_sel_hi:[1,0] neg_lo:[0,1] neg_hi:[0,1]
	v_pk_add_f32 v[126:127], v[4:5], v[128:129] op_sel_hi:[1,0] neg_lo:[0,1] neg_hi:[0,1]
	v_pk_add_f32 v[10:11], v[10:11], v[130:131] op_sel_hi:[1,0] neg_lo:[0,1] neg_hi:[0,1]
	v_pk_add_f32 v[8:9], v[8:9], v[132:133] op_sel_hi:[1,0] neg_lo:[0,1] neg_hi:[0,1]
	v_pk_add_f32 v[12:13], v[12:13], v[134:135] op_sel_hi:[1,0] neg_lo:[0,1] neg_hi:[0,1]
	v_div_fixup_f32 v221, v24, v70, 1.0
	v_div_fmas_f32 v24, v65, v108, v57
	v_lshlrev_b32_e32 v194, 16, v120
	v_and_b32_e32 v120, 0xffff0000, v120
	v_lshlrev_b32_e32 v200, 16, v122
	v_and_b32_e32 v122, 0xffff0000, v122
	v_lshlrev_b32_e32 v197, 16, v129
	v_and_b32_e32 v199, 0xffff0000, v129
	v_lshlrev_b32_e32 v79, 16, v143
	v_and_b32_e32 v77, 0xffff0000, v143
	s_waitcnt vmcnt(2)
	v_lshlrev_b32_e32 v67, 16, v145
	v_and_b32_e32 v57, 0xffff0000, v145
	v_fma_f32 v143, v211, v2, -v190
	v_fma_f32 v145, v211, v14, -v192
	v_pk_add_f32 v[128:129], v[2:3], v[136:137] op_sel_hi:[1,0] neg_lo:[0,1] neg_hi:[0,1]
	v_pk_add_f32 v[14:15], v[14:15], v[138:139] op_sel_hi:[1,0] neg_lo:[0,1] neg_hi:[0,1]
	v_cvt_pk_bf16_f32 v2, v131, v133
	v_cvt_pk_bf16_f32 v3, v135, v137
	v_cvt_pk_bf16_f32 v4, v139, v141
	v_cvt_pk_bf16_f32 v5, v143, v145
	v_mov_b32_e32 v35, v23
	v_mov_b32_e32 v7, v23
	v_mov_b32_e32 v127, v23
	v_mov_b32_e32 v11, v23
	v_mov_b32_e32 v9, v23
	v_mov_b32_e32 v13, v23
	v_div_fixup_f32 v223, v24, v71, 1.0
	v_lshlrev_b32_e32 v112, 16, v42
	v_and_b32_e32 v98, 0xffff0000, v42
	v_lshlrev_b32_e32 v110, 16, v43
	v_and_b32_e32 v100, 0xffff0000, v43
	v_lshlrev_b32_e32 v42, 16, v92
	v_and_b32_e32 v43, 0xffff0000, v92
	v_lshlrev_b32_e32 v26, 16, v93
	v_and_b32_e32 v24, 0xffff0000, v93
	v_lshlrev_b32_e32 v85, 16, v140
	v_and_b32_e32 v71, 0xffff0000, v140
	v_lshlrev_b32_e32 v81, 16, v142
	v_and_b32_e32 v75, 0xffff0000, v142
	v_lshlrev_b32_e32 v69, 16, v144
	v_and_b32_e32 v55, 0xffff0000, v144
	v_lshlrev_b32_e32 v65, 16, v146
	v_and_b32_e32 v59, 0xffff0000, v146
	s_waitcnt vmcnt(1)
	v_lshlrev_b32_e32 v92, 16, v148
	v_and_b32_e32 v93, 0xffff0000, v148
	v_lshlrev_b32_e32 v96, 16, v150
	v_and_b32_e32 v97, 0xffff0000, v150
	v_mul_f32_e32 v140, v23, v195
	v_mul_f32_e32 v142, v23, v121
	v_mul_f32_e32 v144, v23, v197
	v_mul_f32_e32 v146, v23, v199
	v_mul_f32_e32 v148, v23, v201
	v_mul_f32_e32 v150, v23, v123
	v_mov_b32_e32 v129, v23
	v_mov_b32_e32 v15, v23
	global_store_dwordx4 v[16:17], v[2:5], off offset:-2048
	v_pk_add_f32 v[10:11], v[10:11], v[198:199]
	v_pk_add_f32 v[8:9], v[8:9], v[200:201]
	v_pk_add_f32 v[2:3], v[34:35], v[194:195]
	v_pk_add_f32 v[4:5], v[6:7], v[120:121]
	v_pk_add_f32 v[6:7], v[126:127], v[196:197]
	v_pk_add_f32 v[12:13], v[12:13], v[122:123]
	v_lshlrev_b32_e32 v108, 16, v44
	v_and_b32_e32 v102, 0xffff0000, v44
	v_lshlrev_b32_e32 v106, 16, v45
	v_and_b32_e32 v104, 0xffff0000, v45
	v_lshlrev_b32_e32 v84, 16, v46
	v_and_b32_e32 v70, 0xffff0000, v46
	v_lshlrev_b32_e32 v80, 16, v48
	v_and_b32_e32 v74, 0xffff0000, v48
	v_lshlrev_b32_e32 v78, 16, v49
	v_and_b32_e32 v76, 0xffff0000, v49
	v_lshlrev_b32_e32 v68, 16, v50
	v_and_b32_e32 v54, 0xffff0000, v50
	v_lshlrev_b32_e32 v64, 16, v52
	v_and_b32_e32 v58, 0xffff0000, v52
	v_lshlrev_b32_e32 v62, 16, v53
	v_and_b32_e32 v60, 0xffff0000, v53
	v_lshlrev_b32_e32 v50, 16, v89
	v_and_b32_e32 v46, 0xffff0000, v89
	v_lshlrev_b32_e32 v44, 16, v86
	v_and_b32_e32 v45, 0xffff0000, v86
	v_lshlrev_b32_e32 v48, 16, v87
	v_and_b32_e32 v49, 0xffff0000, v87
	v_lshlrev_b32_e32 v52, 16, v88
	v_and_b32_e32 v53, 0xffff0000, v88
	s_waitcnt vmcnt(1)
	v_lshlrev_b32_e32 v86, 16, v152
	v_and_b32_e32 v87, 0xffff0000, v152
	v_lshlrev_b32_e32 v88, 16, v154
	v_and_b32_e32 v89, 0xffff0000, v154
	v_mul_f32_e32 v152, v23, v203
	v_mul_f32_e32 v154, v23, v205
	v_pk_add_f32 v[16:17], v[128:129], v[202:203]
	v_pk_add_f32 v[14:15], v[14:15], v[204:205]
	v_fma_f32 v125, v21, v4, -v120
	v_fma_f32 v126, v21, v6, -v196
	v_fma_f32 v127, v21, v10, -v198
	v_fma_f32 v128, v21, v8, -v200
	v_fma_f32 v122, v21, v12, -v122
	v_pk_add_f32 v[34:35], v[2:3], v[140:141] op_sel_hi:[1,0] neg_lo:[0,1] neg_hi:[0,1]
	v_pk_add_f32 v[120:121], v[4:5], v[142:143] op_sel_hi:[1,0] neg_lo:[0,1] neg_hi:[0,1]
	v_pk_add_f32 v[6:7], v[6:7], v[144:145] op_sel_hi:[1,0] neg_lo:[0,1] neg_hi:[0,1]
	v_pk_add_f32 v[10:11], v[10:11], v[146:147] op_sel_hi:[1,0] neg_lo:[0,1] neg_hi:[0,1]
	v_pk_add_f32 v[8:9], v[8:9], v[148:149] op_sel_hi:[1,0] neg_lo:[0,1] neg_hi:[0,1]
	v_pk_add_f32 v[12:13], v[12:13], v[150:151] op_sel_hi:[1,0] neg_lo:[0,1] neg_hi:[0,1]
	v_lshlrev_b32_e32 v160, 16, v38
	v_and_b32_e32 v162, 0xffff0000, v38
	v_lshlrev_b32_e32 v164, 16, v39
	v_and_b32_e32 v166, 0xffff0000, v39
	v_lshlrev_b32_e32 v168, 16, v40
	v_and_b32_e32 v170, 0xffff0000, v40
	v_fma_f32 v123, v21, v2, -v194
	v_fma_f32 v129, v21, v16, -v202
	v_fma_f32 v21, v21, v14, -v204
	v_pk_add_f32 v[16:17], v[16:17], v[152:153] op_sel_hi:[1,0] neg_lo:[0,1] neg_hi:[0,1]
	v_pk_add_f32 v[14:15], v[14:15], v[154:155] op_sel_hi:[1,0] neg_lo:[0,1] neg_hi:[0,1]
	v_cvt_pk_bf16_f32 v2, v123, v125
	v_cvt_pk_bf16_f32 v3, v126, v127
	v_cvt_pk_bf16_f32 v4, v128, v122
	v_cvt_pk_bf16_f32 v5, v129, v21
	v_mov_b32_e32 v35, v23
	v_mov_b32_e32 v121, v23
	v_mov_b32_e32 v7, v23
	v_mov_b32_e32 v11, v23
	v_mov_b32_e32 v9, v23
	v_mov_b32_e32 v13, v23
	v_lshlrev_b32_e32 v172, 16, v41
	v_and_b32_e32 v174, 0xffff0000, v41
	v_mul_f32_e32 v206, v23, v161
	v_mul_f32_e32 v208, v23, v163
	v_mul_f32_e32 v210, v23, v165
	v_mul_f32_e32 v212, v23, v167
	v_mul_f32_e32 v214, v23, v169
	v_mul_f32_e32 v216, v23, v171
	v_mov_b32_e32 v17, v23
	v_mov_b32_e32 v15, v23
	global_store_dwordx4 v[18:19], v[2:5], off offset:-4096
	v_pk_add_f32 v[6:7], v[6:7], v[164:165]
	v_pk_add_f32 v[10:11], v[10:11], v[166:167]
	v_pk_add_f32 v[2:3], v[34:35], v[160:161]
	v_pk_add_f32 v[4:5], v[120:121], v[162:163]
	v_pk_add_f32 v[8:9], v[8:9], v[168:169]
	v_pk_add_f32 v[12:13], v[12:13], v[170:171]
	v_mul_f32_e32 v218, v23, v173
	v_mul_f32_e32 v220, v23, v175
	v_pk_add_f32 v[16:17], v[16:17], v[172:173]
	v_pk_add_f32 v[14:15], v[14:15], v[174:175]
	v_fma_f32 v122, v213, v6, -v164
	v_fma_f32 v123, v213, v10, -v166
	v_fma_f32 v125, v213, v8, -v168
	v_fma_f32 v126, v213, v12, -v170
	v_pk_add_f32 v[34:35], v[2:3], v[206:207] op_sel_hi:[1,0] neg_lo:[0,1] neg_hi:[0,1]
	v_pk_add_f32 v[120:121], v[4:5], v[208:209] op_sel_hi:[1,0] neg_lo:[0,1] neg_hi:[0,1]
	v_pk_add_f32 v[6:7], v[6:7], v[210:211] op_sel_hi:[1,0] neg_lo:[0,1] neg_hi:[0,1]
	v_pk_add_f32 v[10:11], v[10:11], v[212:213] op_sel_hi:[1,0] neg_lo:[0,1] neg_hi:[0,1]
	v_pk_add_f32 v[8:9], v[8:9], v[214:215] op_sel_hi:[1,0] neg_lo:[0,1] neg_hi:[0,1]
	v_pk_add_f32 v[12:13], v[12:13], v[216:217] op_sel_hi:[1,0] neg_lo:[0,1] neg_hi:[0,1]
	v_fma_f32 v21, v213, v2, -v160
	v_fma_f32 v23, v213, v4, -v162
	v_fma_f32 v127, v213, v16, -v172
	v_fma_f32 v128, v213, v14, -v174
	v_pk_add_f32 v[16:17], v[16:17], v[218:219] op_sel_hi:[1,0] neg_lo:[0,1] neg_hi:[0,1]
	v_pk_add_f32 v[14:15], v[14:15], v[220:221] op_sel_hi:[1,0] neg_lo:[0,1] neg_hi:[0,1]
	v_cvt_pk_bf16_f32 v2, v21, v23
	v_cvt_pk_bf16_f32 v3, v122, v123
	v_cvt_pk_bf16_f32 v4, v125, v126
	v_cvt_pk_bf16_f32 v5, v127, v128
	v_mov_b32_e32 v35, v185
	v_mov_b32_e32 v121, v185
	v_mov_b32_e32 v7, v185
	v_mov_b32_e32 v11, v185
	v_mov_b32_e32 v9, v185
	v_mov_b32_e32 v13, v185
	v_mul_f32_e32 v222, v185, v113
	v_mul_f32_e32 v224, v185, v99
	v_mul_f32_e32 v226, v185, v111
	v_mul_f32_e32 v228, v185, v101
	v_mul_f32_e32 v230, v185, v109
	v_mul_f32_e32 v232, v185, v103
	v_mov_b32_e32 v17, v185
	v_mov_b32_e32 v15, v185
	global_store_dwordx4 v[18:19], v[2:5], off offset:-2048
	v_pk_add_f32 v[6:7], v[6:7], v[110:111]
	v_pk_add_f32 v[10:11], v[10:11], v[100:101]
	v_pk_add_f32 v[2:3], v[34:35], v[112:113]
	v_pk_add_f32 v[4:5], v[120:121], v[98:99]
	v_pk_add_f32 v[8:9], v[8:9], v[108:109]
	v_pk_add_f32 v[12:13], v[12:13], v[102:103]
	v_mul_f32_e32 v234, v185, v107
	v_mul_f32_e32 v236, v185, v105
	v_pk_add_f32 v[16:17], v[16:17], v[106:107]
	v_pk_add_f32 v[14:15], v[14:15], v[104:105]
	v_fma_f32 v23, v215, v4, -v98
	v_fma_f32 v101, v215, v6, -v110
	v_fma_f32 v100, v215, v10, -v100
	v_fma_f32 v103, v215, v8, -v108
	v_fma_f32 v102, v215, v12, -v102
	v_pk_add_f32 v[34:35], v[2:3], v[222:223] op_sel_hi:[1,0] neg_lo:[0,1] neg_hi:[0,1]
	v_pk_add_f32 v[98:99], v[4:5], v[224:225] op_sel_hi:[1,0] neg_lo:[0,1] neg_hi:[0,1]
	v_pk_add_f32 v[6:7], v[6:7], v[226:227] op_sel_hi:[1,0] neg_lo:[0,1] neg_hi:[0,1]
	v_pk_add_f32 v[10:11], v[10:11], v[228:229] op_sel_hi:[1,0] neg_lo:[0,1] neg_hi:[0,1]
	v_pk_add_f32 v[8:9], v[8:9], v[230:231] op_sel_hi:[1,0] neg_lo:[0,1] neg_hi:[0,1]
	v_pk_add_f32 v[12:13], v[12:13], v[232:233] op_sel_hi:[1,0] neg_lo:[0,1] neg_hi:[0,1]
	v_lshlrev_b32_e32 v82, 16, v47
	v_and_b32_e32 v72, 0xffff0000, v47
	v_fma_f32 v21, v215, v2, -v112
	v_fma_f32 v105, v215, v16, -v106
	v_fma_f32 v104, v215, v14, -v104
	v_pk_add_f32 v[16:17], v[16:17], v[234:235] op_sel_hi:[1,0] neg_lo:[0,1] neg_hi:[0,1]
	v_pk_add_f32 v[14:15], v[14:15], v[236:237] op_sel_hi:[1,0] neg_lo:[0,1] neg_hi:[0,1]
	v_cvt_pk_bf16_f32 v2, v21, v23
	v_cvt_pk_bf16_f32 v3, v101, v100
	v_cvt_pk_bf16_f32 v4, v103, v102
	v_cvt_pk_bf16_f32 v5, v105, v104
	v_mov_b32_e32 v35, v207
	v_mov_b32_e32 v99, v207
	v_mov_b32_e32 v7, v207
	v_mov_b32_e32 v11, v207
	v_mov_b32_e32 v9, v207
	v_mov_b32_e32 v13, v207
	v_mul_f32_e32 v238, v207, v85
	v_mul_f32_e32 v240, v207, v71
	v_mul_f32_e32 v242, v207, v83
	v_mul_f32_e32 v244, v207, v73
	v_mul_f32_e32 v246, v207, v81
	v_mul_f32_e32 v248, v207, v75
	v_mov_b32_e32 v17, v207
	v_mov_b32_e32 v15, v207
	global_store_dwordx4 v[18:19], v[2:5], off
	v_pk_add_f32 v[6:7], v[6:7], v[82:83]
	v_pk_add_f32 v[10:11], v[10:11], v[72:73]
	v_pk_add_f32 v[2:3], v[34:35], v[84:85]
	v_pk_add_f32 v[4:5], v[98:99], v[70:71]
	v_pk_add_f32 v[8:9], v[8:9], v[80:81]
	v_pk_add_f32 v[12:13], v[12:13], v[74:75]
	v_mul_f32_e32 v176, v207, v79
	v_mul_f32_e32 v178, v207, v77
	v_pk_add_f32 v[16:17], v[16:17], v[78:79]
	v_pk_add_f32 v[14:15], v[14:15], v[76:77]
	v_fma_f32 v23, v217, v4, -v70
	v_fma_f32 v70, v217, v6, -v82
	v_fma_f32 v71, v217, v10, -v72
	v_fma_f32 v72, v217, v8, -v80
	v_fma_f32 v73, v217, v12, -v74
	v_pk_add_f32 v[18:19], v[2:3], v[238:239] op_sel_hi:[1,0] neg_lo:[0,1] neg_hi:[0,1]
	v_pk_add_f32 v[34:35], v[4:5], v[240:241] op_sel_hi:[1,0] neg_lo:[0,1] neg_hi:[0,1]
	v_pk_add_f32 v[6:7], v[6:7], v[242:243] op_sel_hi:[1,0] neg_lo:[0,1] neg_hi:[0,1]
	v_pk_add_f32 v[10:11], v[10:11], v[244:245] op_sel_hi:[1,0] neg_lo:[0,1] neg_hi:[0,1]
	v_pk_add_f32 v[8:9], v[8:9], v[246:247] op_sel_hi:[1,0] neg_lo:[0,1] neg_hi:[0,1]
	v_pk_add_f32 v[12:13], v[12:13], v[248:249] op_sel_hi:[1,0] neg_lo:[0,1] neg_hi:[0,1]
	v_lshlrev_b32_e32 v66, 16, v51
	v_and_b32_e32 v56, 0xffff0000, v51
	v_fma_f32 v21, v217, v2, -v84
	v_fma_f32 v74, v217, v16, -v78
	v_fma_f32 v75, v217, v14, -v76
	v_pk_add_f32 v[16:17], v[16:17], v[176:177] op_sel_hi:[1,0] neg_lo:[0,1] neg_hi:[0,1]
	v_pk_add_f32 v[14:15], v[14:15], v[178:179] op_sel_hi:[1,0] neg_lo:[0,1] neg_hi:[0,1]
	v_cvt_pk_bf16_f32 v2, v21, v23
	v_cvt_pk_bf16_f32 v3, v70, v71
	v_cvt_pk_bf16_f32 v4, v72, v73
	v_cvt_pk_bf16_f32 v5, v74, v75
	v_mov_b32_e32 v19, v209
	v_mov_b32_e32 v35, v209
	v_mov_b32_e32 v7, v209
	v_mov_b32_e32 v11, v209
	v_mov_b32_e32 v9, v209
	v_mov_b32_e32 v13, v209
	v_lshlrev_b32_e32 v63, 16, v147
	v_and_b32_e32 v61, 0xffff0000, v147
	v_mov_b32_e32 v17, v209
	v_mov_b32_e32 v15, v209
	global_store_dwordx4 v[36:37], v[2:5], off offset:-2048
	v_pk_add_f32 v[36:37], v[18:19], v[68:69]
	v_pk_add_f32 v[70:71], v[10:11], v[56:57]
	v_pk_mul_f32 v[2:3], v[18:19], v[68:69]
	v_pk_add_f32 v[4:5], v[34:35], v[54:55]
	v_pk_mul_f32 v[18:19], v[34:35], v[54:55]
	v_pk_add_f32 v[34:35], v[6:7], v[66:67]
	v_pk_mul_f32 v[6:7], v[6:7], v[66:67]
	v_pk_mul_f32 v[10:11], v[10:11], v[56:57]
	v_pk_add_f32 v[72:73], v[8:9], v[64:65]
	v_pk_mul_f32 v[8:9], v[8:9], v[64:65]
	v_pk_add_f32 v[74:75], v[12:13], v[58:59]
	v_pk_mul_f32 v[12:13], v[12:13], v[58:59]
	v_mul_f32_e32 v180, v209, v63
	v_mul_f32_e32 v182, v209, v61
	v_pk_add_f32 v[16:17], v[16:17], v[62:63]
	v_pk_add_f32 v[14:15], v[14:15], v[60:61]
	v_fma_f32 v2, v219, v36, -v68
	v_fma_f32 v6, v219, v34, -v66
	v_fma_f32 v8, v219, v70, -v56
	v_mov_b32_e32 v37, v4
	v_mov_b32_e32 v18, v3
	v_mov_b32_e32 v35, v70
	v_mov_b32_e32 v10, v7
	v_mov_b32_e32 v73, v74
	v_mov_b32_e32 v12, v9
	v_fma_f32 v5, v219, v4, -v54
	v_fma_f32 v54, v219, v16, -v62
	v_fma_f32 v55, v219, v14, -v60
	v_pk_add_f32 v[16:17], v[16:17], v[180:181] op_sel_hi:[1,0] neg_lo:[0,1] neg_hi:[0,1]
	v_pk_add_f32 v[14:15], v[14:15], v[182:183] op_sel_hi:[1,0] neg_lo:[0,1] neg_hi:[0,1]
	v_cvt_pk_bf16_f32 v2, v2, v5
	v_cvt_pk_bf16_f32 v3, v6, v8
	v_pk_add_f32 v[6:7], v[36:37], v[18:19] neg_lo:[0,1] neg_hi:[0,1]
	v_pk_add_f32 v[8:9], v[34:35], v[10:11] neg_lo:[0,1] neg_hi:[0,1]
	v_pk_add_f32 v[10:11], v[72:73], v[12:13] neg_lo:[0,1] neg_hi:[0,1]
	v_lshlrev_b32_e32 v51, 16, v151
	v_and_b32_e32 v47, 0xffff0000, v151
	v_lshlrev_b32_e32 v94, 16, v149
	v_and_b32_e32 v95, 0xffff0000, v149
	v_fma_f32 v21, v219, v72, -v64
	v_fma_f32 v23, v219, v74, -v58
	v_cvt_pk_bf16_f32 v4, v21, v23
	v_cvt_pk_bf16_f32 v5, v54, v55
	v_mov_b32_e32 v17, v22
	v_mov_b32_e32 v15, v22
	v_pk_add_f32 v[6:7], v[6:7], v[44:45]
	v_pk_add_f32 v[8:9], v[8:9], v[48:49]
	v_pk_add_f32 v[10:11], v[10:11], v[52:53]
	v_mul_f32_e32 v186, v22, v51
	v_mul_f32_e32 v124, v22, v47
	global_store_dwordx4 v[0:1], v[2:5], off offset:-4096
	v_fma_f32 v19, v221, v7, -v45
	v_pk_fma_f32 v[12:13], v[22:23], v[92:93], v[6:7] op_sel_hi:[0,1,1] neg_lo:[1,0,0] neg_hi:[1,0,0]
	v_pk_add_f32 v[2:3], v[16:17], v[50:51]
	v_pk_add_f32 v[4:5], v[14:15], v[46:47]
	v_fma_f32 v7, v221, v8, -v48
	v_fma_f32 v21, v221, v9, -v49
	v_pk_fma_f32 v[8:9], v[22:23], v[94:95], v[8:9] op_sel_hi:[0,1,1] neg_lo:[1,0,0] neg_hi:[1,0,0]
	v_fma_f32 v23, v221, v10, -v52
	v_lshlrev_b32_e32 v38, 16, v90
	v_and_b32_e32 v39, 0xffff0000, v90
	v_lshlrev_b32_e32 v40, 16, v91
	v_and_b32_e32 v41, 0xffff0000, v91
	v_fma_f32 v16, v221, v2, -v50
	v_fma_f32 v34, v221, v11, -v53
	v_pk_fma_f32 v[10:11], v[22:23], v[96:97], v[10:11] op_sel_hi:[0,1,1] neg_lo:[1,0,0] neg_hi:[1,0,0]
	v_pk_add_f32 v[2:3], v[2:3], v[186:187] op_sel_hi:[1,0] neg_lo:[0,1] neg_hi:[0,1]
	v_pk_add_f32 v[14:15], v[4:5], v[124:125] op_sel_hi:[1,0] neg_lo:[0,1] neg_hi:[0,1]
	v_lshlrev_b32_e32 v90, 16, v153
	v_and_b32_e32 v91, 0xffff0000, v153
	v_lshlrev_b32_e32 v27, 16, v155
	v_and_b32_e32 v25, 0xffff0000, v155
	v_fma_f32 v17, v221, v4, -v46
	v_fma_f32 v18, v221, v6, -v44
	v_cvt_pk_bf16_f32 v6, v18, v19
	v_pk_add_f32 v[4:5], v[12:13], v[38:39]
	v_pk_add_f32 v[12:13], v[8:9], v[40:41]
	v_cvt_pk_bf16_f32 v7, v7, v21
	v_pk_add_f32 v[10:11], v[10:11], v[42:43]
	v_cvt_pk_bf16_f32 v8, v23, v34
	v_cvt_pk_bf16_f32 v9, v16, v17
	v_mov_b32_e32 v3, v20
	v_mov_b32_e32 v15, v20
	v_fma_f32 v16, v223, v4, -v38
	v_fma_f32 v17, v223, v5, -v39
	v_pk_fma_f32 v[34:35], v[20:21], v[86:87], v[4:5] op_sel_hi:[0,1,1] neg_lo:[1,0,0] neg_hi:[1,0,0]
	v_pk_fma_f32 v[4:5], v[20:21], v[90:91], v[12:13] op_sel_hi:[0,1,1] neg_lo:[1,0,0] neg_hi:[1,0,0]
	global_store_dwordx4 v[0:1], v[6:9], off offset:-2048
	v_pk_add_f32 v[18:19], v[2:3], v[26:27]
	v_pk_mul_f32 v[2:3], v[2:3], v[26:27]
	v_pk_fma_f32 v[8:9], v[20:21], v[88:89], v[10:11] op_sel_hi:[0,1,1] neg_lo:[1,0,0] neg_hi:[1,0,0]
	v_pk_add_f32 v[6:7], v[14:15], v[24:25]
	v_pk_mul_f32 v[20:21], v[14:15], v[24:25]
	v_fma_f32 v2, v223, v18, -v26
	v_mov_b32_e32 v19, v6
	v_mov_b32_e32 v20, v3
	s_add_i32 s53, s53, 8
	v_fma_f32 v22, v223, v12, -v40
	v_fma_f32 v23, v223, v13, -v41
	v_fma_f32 v12, v223, v10, -v42
	v_fma_f32 v13, v223, v11, -v43
	v_cvt_pk_bf16_f32 v14, v16, v17
	v_cvt_pk_bf16_f32 v15, v22, v23
	v_cvt_pk_bf16_f32 v16, v12, v13
	v_fma_f32 v7, v223, v6, -v24
	v_cvt_pk_bf16_f32 v17, v2, v7
	v_pk_add_f32 v[2:3], v[18:19], v[20:21] neg_lo:[0,1] neg_hi:[0,1]
	s_cmp_gt_u32 s53, 23
	v_mov_b32_e32 v6, v35
	v_mov_b32_e32 v10, v5
	v_mov_b32_e32 v12, v9
	global_store_dwordx4 v[0:1], v[14:17], off
	v_lshl_add_u64 v[0:1], v[0:1], 0, s[46:47]
	s_nop 0
	v_mov_b32_e32 v14, v3
	s_cbranch_scc0 .LBB0_938
	v_add_u32_e32 v184, s33, v184
	v_cmp_lt_i32_e32 vcc, s52, v184
	s_or_b64 s[44:45], vcc, s[44:45]
	s_andn2_b64 exec, exec, s[44:45]
	s_cbranch_execnz .LBB0_937

.LBB0_1258:
	s_or_b64 exec, exec, s[4:5]
	s_waitcnt lgkmcnt(0)
	v_lshrrev_b32_e32 v0, 4, v157
	v_and_b32_e32 v0, 60, v0
	v_lshl_add_u32 v16, s2, 5, v0
	s_mov_b32 s2, 0x8000
	v_cmp_gt_i32_e32 vcc, s2, v16
	s_barrier
	s_and_saveexec_b64 s[2:3], vcc
	s_cbranch_execz .LBB0_1261
	s_load_dwordx4 s[4:7], s[0:1], 0x70
	s_load_dwordx2 s[2:3], s[0:1], 0x80
	v_lshlrev_b32_e32 v20, 5, v156
	v_ashrrev_i32_e32 v17, 31, v16
	v_lshlrev_b64 v[18:19], 12, v[16:17]
	s_waitcnt lgkmcnt(0)
	global_load_dwordx4 v[0:3], v20, s[4:5] offset:16 nt
	global_load_dwordx4 v[4:7], v20, s[4:5] nt
	global_load_dwordx4 v[8:11], v20, s[4:5] offset:2064 nt
	global_load_dwordx4 v[12:15], v20, s[4:5] offset:2048 nt
	v_or_b32_e32 v18, v18, v20
	v_lshl_add_u64 v[18:19], s[6:7], 0, v[18:19]
	s_mov_b64 s[0:1], 0x3810
	v_lshlrev_b64 v[22:23], 11, v[16:17]
	v_lshl_add_u64 v[18:19], v[18:19], 0, s[0:1]
	v_lshlrev_b64 v[20:21], 4, v[16:17]
	v_or_b32_e32 v22, v22, v158
	s_mov_b64 s[4:5], 0
	s_mov_b64 s[6:7], 0x100000
	v_mov_b32_e32 v17, 0x358637bd
	s_mov_b32 s8, 0x6001000
	s_movk_i32 s9, 0xd000
	s_movk_i32 s10, 0xe000
	s_movk_i32 s11, 0xf000
	s_movk_i32 s12, 0x7fff
.LBB0_1260:
	v_add_co_u32_e32 v24, vcc, s9, v18
	v_lshl_add_u64 v[30:31], s[2:3], 0, v[22:23]
	s_nop 0
	v_addc_co_u32_e32 v25, vcc, -1, v19, vcc
	v_add_co_u32_e32 v26, vcc, s10, v18
	v_lshl_add_u64 v[28:29], s[2:3], 0, v[20:21]
	s_nop 0
	v_addc_co_u32_e32 v27, vcc, -1, v19, vcc
	v_add_co_u32_e32 v32, vcc, s11, v18
	v_lshl_add_u64 v[78:79], v[28:29], 0, s[6:7]
	s_nop 0
	v_addc_co_u32_e32 v33, vcc, -1, v19, vcc
	v_add_co_u32_e32 v74, vcc, 0x6000000, v30
	v_add_co_u32_e64 v58, s[0:1], s8, v30
	s_nop 0
	v_addc_co_u32_e32 v75, vcc, 0, v31, vcc
	v_add_co_u32_e32 v80, vcc, 0x100000, v28
	v_addc_co_u32_e64 v59, s[0:1], 0, v31, s[0:1]
	global_load_dwordx4 v[34:37], v[78:79], off offset:16 nt
	global_load_dwordx4 v[38:41], v[78:79], off offset:32 nt
	global_load_dwordx4 v[42:45], v[58:59], off nt
	global_load_dwordx4 v[46:49], v[58:59], off offset:1024 nt
	global_load_dwordx4 v[50:53], v[58:59], off offset:2048 nt
	global_load_dwordx4 v[54:57], v[58:59], off offset:3072 nt
	v_addc_co_u32_e32 v81, vcc, 0, v29, vcc
	global_load_dwordx4 v[58:61], v[74:75], off nt
	global_load_dwordx4 v[62:65], v[74:75], off offset:1024 nt
	global_load_dwordx4 v[66:69], v[74:75], off offset:2048 nt
	global_load_dwordx4 v[70:73], v[74:75], off offset:3072 nt
	global_load_dwordx4 v[28:31], v[80:81], off nt
	s_nop 0
	global_load_dwordx4 v[74:77], v[78:79], off offset:48 nt
	v_add_u32_e32 v16, s34, v16
	v_cmp_lt_i32_e64 s[0:1], s12, v16
	v_lshl_add_u64 v[20:21], v[20:21], 0, s[36:37]
	v_lshl_add_u64 v[22:23], v[22:23], 0, s[38:39]
	s_or_b64 s[4:5], s[0:1], s[4:5]
	s_waitcnt vmcnt(11)
	v_mov_b32_e32 v78, v35
	v_mov_b32_e32 v79, v36
	v_mov_b32_e32 v35, v37
	s_waitcnt vmcnt(10)
	v_mov_b32_e32 v36, v39
	v_mov_b32_e32 v37, v40
	v_mov_b32_e32 v39, v41
	s_waitcnt vmcnt(7)
	v_lshlrev_b32_e32 v90, 16, v52
	v_and_b32_e32 v91, 0xffff0000, v52
	v_lshlrev_b32_e32 v92, 16, v53
	v_and_b32_e32 v93, 0xffff0000, v53
	s_waitcnt vmcnt(6)
	v_lshlrev_b32_e32 v94, 16, v54
	v_and_b32_e32 v95, 0xffff0000, v54
	v_lshlrev_b32_e32 v96, 16, v55
	v_and_b32_e32 v97, 0xffff0000, v55
	v_pk_add_f32 v[34:35], v[78:79], v[34:35]
	v_pk_add_f32 v[36:37], v[36:37], v[38:39]
	s_waitcnt vmcnt(3)
	v_lshlrev_b32_e32 v52, 16, v68
	v_and_b32_e32 v53, 0xffff0000, v68
	v_lshlrev_b32_e32 v54, 16, v69
	v_and_b32_e32 v55, 0xffff0000, v69
	s_waitcnt vmcnt(1)
	v_mov_b32_e32 v68, v29
	v_mov_b32_e32 v69, v30
	v_mov_b32_e32 v29, v31
	v_add_f32_e32 v34, v34, v35
	v_add_f32_e32 v35, v36, v37
	s_waitcnt vmcnt(0)
	v_mov_b32_e32 v30, v75
	v_mov_b32_e32 v31, v76
	v_mov_b32_e32 v75, v77
	v_pk_add_f32 v[28:29], v[68:69], v[28:29]
	v_fmamk_f32 v34, v34, 0x3a800000, v17
	v_fmamk_f32 v35, v35, 0x3a800000, v17
	v_pk_add_f32 v[30:31], v[30:31], v[74:75]
	v_add_f32_e32 v29, v28, v29
	v_rsq_f32_e32 v28, v34
	v_rsq_f32_e32 v34, v35
	v_add_f32_e32 v30, v30, v31
	v_fmamk_f32 v29, v29, 0x3a800000, v17
	v_fmamk_f32 v30, v30, 0x3a800000, v17
	v_rsq_f32_e32 v68, v29
	v_lshlrev_b32_e32 v98, 16, v56
	v_and_b32_e32 v99, 0xffff0000, v56
	v_lshlrev_b32_e32 v100, 16, v57
	v_and_b32_e32 v101, 0xffff0000, v57
	v_lshlrev_b32_e32 v56, 16, v70
	v_and_b32_e32 v57, 0xffff0000, v70
	v_rsq_f32_e32 v70, v30
	v_lshlrev_b32_e32 v40, 16, v42
	v_and_b32_e32 v41, 0xffff0000, v42
	v_lshlrev_b32_e32 v42, 16, v43
	v_and_b32_e32 v43, 0xffff0000, v43
	v_lshlrev_b32_e32 v80, 16, v44
	v_and_b32_e32 v81, 0xffff0000, v44
	v_lshlrev_b32_e32 v44, 16, v45
	v_and_b32_e32 v45, 0xffff0000, v45
	v_lshlrev_b32_e32 v82, 16, v46
	v_and_b32_e32 v83, 0xffff0000, v46
	v_lshlrev_b32_e32 v46, 16, v47
	v_and_b32_e32 v47, 0xffff0000, v47
	v_lshlrev_b32_e32 v84, 16, v48
	v_and_b32_e32 v85, 0xffff0000, v48
	v_lshlrev_b32_e32 v86, 16, v50
	v_and_b32_e32 v87, 0xffff0000, v50
	v_lshlrev_b32_e32 v88, 16, v51
	v_and_b32_e32 v89, 0xffff0000, v51
	v_lshlrev_b32_e32 v78, 16, v58
	v_and_b32_e32 v79, 0xffff0000, v58
	v_lshlrev_b32_e32 v102, 16, v59
	v_and_b32_e32 v103, 0xffff0000, v59
	v_lshlrev_b32_e32 v104, 16, v60
	v_and_b32_e32 v105, 0xffff0000, v60
	v_lshlrev_b32_e32 v106, 16, v61
	v_and_b32_e32 v107, 0xffff0000, v61
	v_lshlrev_b32_e32 v38, 16, v66
	v_and_b32_e32 v39, 0xffff0000, v66
	v_lshlrev_b32_e32 v50, 16, v67
	v_and_b32_e32 v51, 0xffff0000, v67
	v_lshlrev_b32_e32 v58, 16, v71
	v_and_b32_e32 v59, 0xffff0000, v71
	v_lshlrev_b32_e32 v60, 16, v72
	v_and_b32_e32 v61, 0xffff0000, v72
	v_lshlrev_b32_e32 v66, 16, v73
	v_and_b32_e32 v67, 0xffff0000, v73
	v_lshlrev_b32_e32 v48, 16, v49
	v_and_b32_e32 v49, 0xffff0000, v49
	v_pk_mul_f32 v[36:37], v[28:29], v[38:39] op_sel_hi:[0,1]
	v_pk_mul_f32 v[30:31], v[28:29], v[50:51] op_sel_hi:[0,1]
	v_pk_mul_f32 v[38:39], v[28:29], v[52:53] op_sel_hi:[0,1]
	v_pk_mul_f32 v[50:51], v[28:29], v[54:55] op_sel_hi:[0,1]
	v_pk_mul_f32 v[52:53], v[28:29], v[56:57] op_sel_hi:[0,1]
	v_pk_mul_f32 v[54:55], v[28:29], v[58:59] op_sel_hi:[0,1]
	v_pk_mul_f32 v[56:57], v[28:29], v[60:61] op_sel_hi:[0,1]
	v_pk_mul_f32 v[58:59], v[28:29], v[66:67] op_sel_hi:[0,1]
	v_pk_mul_f32 v[60:61], v[34:35], v[40:41] op_sel_hi:[0,1]
	v_pk_mul_f32 v[66:67], v[34:35], v[42:43] op_sel_hi:[0,1]
	v_pk_mul_f32 v[72:73], v[34:35], v[80:81] op_sel_hi:[0,1]
	v_pk_mul_f32 v[74:75], v[34:35], v[44:45] op_sel_hi:[0,1]
	v_pk_mul_f32 v[76:77], v[34:35], v[82:83] op_sel_hi:[0,1]
	v_pk_mul_f32 v[80:81], v[34:35], v[46:47] op_sel_hi:[0,1]
	v_pk_mul_f32 v[82:83], v[34:35], v[84:85] op_sel_hi:[0,1]
	v_lshlrev_b32_e32 v108, 16, v62
	v_and_b32_e32 v109, 0xffff0000, v62
	v_lshlrev_b32_e32 v62, 16, v63
	v_and_b32_e32 v63, 0xffff0000, v63
	v_lshlrev_b32_e32 v110, 16, v64
	v_and_b32_e32 v111, 0xffff0000, v64
	v_lshlrev_b32_e32 v64, 16, v65
	v_and_b32_e32 v65, 0xffff0000, v65
	v_pk_mul_f32 v[84:85], v[34:35], v[48:49] op_sel_hi:[0,1]
	v_pk_mul_f32 v[30:31], v[6:7], v[30:31]
	v_pk_mul_f32 v[28:29], v[4:5], v[36:37]
	v_pk_mul_f32 v[36:37], v[2:3], v[50:51]
	v_pk_mul_f32 v[34:35], v[0:1], v[38:39]
	v_pk_mul_f32 v[40:41], v[14:15], v[54:55]
	v_pk_mul_f32 v[38:39], v[12:13], v[52:53]
	v_pk_mul_f32 v[44:45], v[10:11], v[58:59]
	v_pk_mul_f32 v[42:43], v[8:9], v[56:57]
	v_pk_mul_f32 v[48:49], v[6:7], v[66:67]
	v_pk_mul_f32 v[46:47], v[4:5], v[60:61]
	v_pk_mul_f32 v[52:53], v[2:3], v[74:75]
	v_pk_mul_f32 v[50:51], v[0:1], v[72:73]
	v_pk_mul_f32 v[56:57], v[14:15], v[80:81]
	v_pk_mul_f32 v[54:55], v[12:13], v[76:77]
	v_pk_mul_f32 v[58:59], v[8:9], v[82:83]
	v_pk_mul_f32 v[66:67], v[68:69], v[78:79] op_sel_hi:[0,1]
	v_pk_mul_f32 v[72:73], v[68:69], v[102:103] op_sel_hi:[0,1]
	v_pk_mul_f32 v[60:61], v[10:11], v[84:85]
	v_pk_mul_f32 v[74:75], v[68:69], v[104:105] op_sel_hi:[0,1]
	v_pk_mul_f32 v[76:77], v[68:69], v[106:107] op_sel_hi:[0,1]
	v_pk_mul_f32 v[78:79], v[68:69], v[108:109] op_sel_hi:[0,1]
	v_pk_mul_f32 v[62:63], v[68:69], v[62:63] op_sel_hi:[0,1]
	v_pk_mul_f32 v[80:81], v[68:69], v[110:111] op_sel_hi:[0,1]
	v_pk_mul_f32 v[64:65], v[68:69], v[64:65] op_sel_hi:[0,1]
	global_store_dwordx4 v[26:27], v[28:31], off offset:-2064 nt
	global_store_dwordx4 v[26:27], v[34:37], off offset:-2048 nt
	global_store_dwordx4 v[26:27], v[38:41], off offset:-16 nt
	global_store_dwordx4 v[26:27], v[42:45], off nt
	global_store_dwordx4 v[32:33], v[46:49], off offset:-2064 nt
	global_store_dwordx4 v[32:33], v[50:53], off offset:-2048 nt
	global_store_dwordx4 v[32:33], v[54:57], off offset:-16 nt
	global_store_dwordx4 v[18:19], v[58:61], off offset:-4096 nt
	v_pk_mul_f32 v[44:45], v[70:71], v[86:87] op_sel_hi:[0,1]
	v_pk_mul_f32 v[46:47], v[70:71], v[88:89] op_sel_hi:[0,1]
	v_pk_mul_f32 v[48:49], v[70:71], v[90:91] op_sel_hi:[0,1]
	v_pk_mul_f32 v[50:51], v[70:71], v[92:93] op_sel_hi:[0,1]
	v_pk_mul_f32 v[52:53], v[70:71], v[94:95] op_sel_hi:[0,1]
	v_pk_mul_f32 v[54:55], v[70:71], v[96:97] op_sel_hi:[0,1]
	v_pk_mul_f32 v[56:57], v[70:71], v[98:99] op_sel_hi:[0,1]
	v_pk_mul_f32 v[58:59], v[70:71], v[100:101] op_sel_hi:[0,1]
	v_pk_mul_f32 v[30:31], v[6:7], v[72:73]
	v_pk_mul_f32 v[28:29], v[4:5], v[66:67]
	v_pk_mul_f32 v[34:35], v[2:3], v[76:77]
	v_pk_mul_f32 v[32:33], v[0:1], v[74:75]
	v_pk_mul_f32 v[38:39], v[14:15], v[62:63]
	v_pk_mul_f32 v[36:37], v[12:13], v[78:79]
	v_pk_mul_f32 v[42:43], v[10:11], v[64:65]
	v_pk_mul_f32 v[40:41], v[8:9], v[80:81]
	v_pk_mul_f32 v[46:47], v[6:7], v[46:47]
	v_pk_mul_f32 v[44:45], v[4:5], v[44:45]
	v_pk_mul_f32 v[50:51], v[2:3], v[50:51]
	v_pk_mul_f32 v[48:49], v[0:1], v[48:49]
	v_pk_mul_f32 v[54:55], v[14:15], v[54:55]
	v_pk_mul_f32 v[52:53], v[12:13], v[52:53]
	v_pk_mul_f32 v[58:59], v[10:11], v[58:59]
	v_pk_mul_f32 v[56:57], v[8:9], v[56:57]
	global_store_dwordx4 v[24:25], v[28:31], off offset:-2064 nt
	global_store_dwordx4 v[24:25], v[32:35], off offset:-2048 nt
	global_store_dwordx4 v[24:25], v[36:39], off offset:-16 nt
	global_store_dwordx4 v[26:27], v[40:43], off offset:-4096 nt
	global_store_dwordx4 v[18:19], v[44:47], off offset:-2064 nt
	global_store_dwordx4 v[18:19], v[48:51], off offset:-2048 nt
	global_store_dwordx4 v[18:19], v[52:55], off offset:-16 nt
	global_store_dwordx4 v[18:19], v[56:59], off nt
	v_lshl_add_u64 v[18:19], v[18:19], 0, s[40:41]
	s_andn2_b64 exec, exec, s[4:5]
	s_cbranch_execnz .LBB0_1260
